# attention item epilogue: output stores widened from 8x dwordx2 to 4x dwordx4 per lane via v_permlane32_swap pairs (asm guide 7.3)
# speedup vs baseline: 1.0033x; 1.0033x over previous
; __device__ __forceinline__ float fast_exp2(float x) { return __builtin_amdgcn_exp2f(x); }
; template <int DQ, int TYPE>
; __device__ __forceinline__ void attn_item(PP p, int layer, int b, int h, int qt, char* lds, const int tid_, unsigned* next_ctr, volatile XLAS unsigned* slot) {
;     ...
;     l_run += __shfl_xor(l_run, 32);
;     float* mrg = (float*)lds;
;     {
;         float* mp = mrg + (size_t)((qg * 2 + kh) * 34) * 64 + lane;
;         if (kh == 0) {
; #pragma unroll
;             for (int t2 = 0; t2 < 2; ++t2)
; #pragma unroll
;                 for (int i = 0; i < 16; ++i) mp[(t2 * 16 + i) * 64] = O[2 + t2][i];
;         } else {
; #pragma unroll
;             for (int t2 = 0; t2 < 2; ++t2)
; #pragma unroll
;                 for (int i = 0; i < 16; ++i) mp[(t2 * 16 + i) * 64] = O[t2][i];
;         }
;         mp[32 * 64] = m_run; mp[33 * 64] = l_run;
;     }
;     __syncthreads();
;     {
;         const float* mp = mrg + (size_t)((qg * 2 + (kh ^ 1)) * 34) * 64 + lane;
;         const float m1 = mp[32 * 64], l1 = mp[33 * 64];
;         const float mt = fmaxf(m_run, m1);
;         const float a0 = fast_exp2(m_run - mt), a1 = fast_exp2(m1 - mt);
;         const float inv = 1.0f / (l_run * a0 + l1 * a1);
;         bf16_t* orow = Op + (size_t)qpos * D;
;     ...
;         if (kh == 0) A_MERGE(0); else A_MERGE(2);
.LBB0_418:
	s_or_b64 exec, exec, s[12:13]
	s_load_dwordx2 s[14:15], s[0:1], 0x98
	s_lshl_b32 s12, s55, 12
	v_and_b32_e32 v2, 64, v224
	v_xor_b32_e32 v0, 32, v224
	v_add_u32_e32 v2, 64, v2
	s_waitcnt lgkmcnt(0)
	s_add_u32 s12, s14, s12
	s_addc_u32 s13, s15, 0
	s_lshl_b32 s14, s57, 1
	s_add_u32 s12, s12, s14
	v_cmp_lt_i32_e32 vcc, v0, v2
	s_addc_u32 s13, s13, 0
	s_lshl_b32 s14, s49, 1
	v_cndmask_b32_e32 v0, v224, v0, vcc
	s_add_i32 s15, s14, s56
	v_lshlrev_b32_e32 v0, 2, v0
	s_mulk_i32 s15, 0x2200
	ds_bpermute_b32 v0, v0, v158
	s_add_i32 s15, s15, 16
	v_lshlrev_b32_e32 v2, 2, v156
	v_add_u32_e32 v3, s15, v2
	s_xor_b32 s15, s56, 1
	s_add_i32 s14, s14, s15
	s_mulk_i32 s14, 0x2200
	v_cndmask_b32_e64 v12, v40, v72, s[52:53]
	v_cndmask_b32_e64 v83, v33, v65, s[52:53]
	v_cndmask_b32_e64 v84, v32, v64, s[52:53]
	s_add_i32 s14, s14, 16
	s_waitcnt lgkmcnt(0)
	v_add_f32_e32 v0, v158, v0
	v_cndmask_b32_e64 v4, v47, v79, s[52:53]
	v_cndmask_b32_e64 v5, v46, v78, s[52:53]
	v_cndmask_b32_e64 v6, v45, v77, s[52:53]
	v_cndmask_b32_e64 v7, v44, v76, s[52:53]
	v_cndmask_b32_e64 v8, v43, v75, s[52:53]
	v_cndmask_b32_e64 v9, v42, v74, s[52:53]
	v_cndmask_b32_e64 v11, v41, v73, s[52:53]
	v_cndmask_b32_e64 v13, v39, v71, s[52:53]
	v_cndmask_b32_e64 v14, v38, v70, s[52:53]
	v_cndmask_b32_e64 v15, v37, v69, s[52:53]
	v_cndmask_b32_e64 v80, v36, v68, s[52:53]
	v_cndmask_b32_e64 v81, v35, v67, s[52:53]
	v_cndmask_b32_e64 v82, v34, v66, s[52:53]
	v_cndmask_b32_e64 v85, v31, v63, s[52:53]
	v_cndmask_b32_e64 v86, v30, v62, s[52:53]
	v_cndmask_b32_e64 v87, v29, v61, s[52:53]
	v_cndmask_b32_e64 v88, v28, v60, s[52:53]
	v_cndmask_b32_e64 v89, v27, v59, s[52:53]
	v_cndmask_b32_e64 v90, v26, v58, s[52:53]
	v_cndmask_b32_e64 v91, v25, v57, s[52:53]
	v_cndmask_b32_e64 v92, v24, v56, s[52:53]
	v_cndmask_b32_e64 v93, v23, v55, s[52:53]
	v_cndmask_b32_e64 v94, v22, v54, s[52:53]
	v_cndmask_b32_e64 v95, v21, v53, s[52:53]
	s_waitcnt vmcnt(3)
	v_cndmask_b32_e64 v96, v20, v52, s[52:53]
	v_cndmask_b32_e64 v97, v19, v51, s[52:53]
	v_cndmask_b32_e64 v98, v18, v50, s[52:53]
	v_cndmask_b32_e64 v99, v17, v49, s[52:53]
	s_waitcnt vmcnt(2)
	v_cndmask_b32_e64 v100, v16, v48, s[52:53]
	ds_write2st64_b32 v3, v84, v83 offset1:1
	ds_write2st64_b32 v3, v82, v81 offset0:2 offset1:3
	ds_write2st64_b32 v3, v80, v15 offset0:4 offset1:5
	ds_write2st64_b32 v3, v14, v13 offset0:6 offset1:7
	ds_write2st64_b32 v3, v12, v11 offset0:8 offset1:9
	ds_write2st64_b32 v3, v9, v8 offset0:10 offset1:11
	ds_write2st64_b32 v3, v7, v6 offset0:12 offset1:13
	ds_write2st64_b32 v3, v5, v4 offset0:14 offset1:15
	ds_write2st64_b32 v3, v100, v99 offset0:16 offset1:17
	ds_write2st64_b32 v3, v98, v97 offset0:18 offset1:19
	ds_write2st64_b32 v3, v96, v95 offset0:20 offset1:21
	ds_write2st64_b32 v3, v94, v93 offset0:22 offset1:23
	ds_write2st64_b32 v3, v92, v91 offset0:24 offset1:25
	ds_write2st64_b32 v3, v90, v89 offset0:26 offset1:27
	ds_write2st64_b32 v3, v88, v87 offset0:28 offset1:29
	ds_write2st64_b32 v3, v86, v85 offset0:30 offset1:31
	ds_write2st64_b32 v3, v168, v0 offset0:32 offset1:33
	v_add_u32_e32 v12, s14, v2
	s_waitcnt lgkmcnt(0)
	s_barrier
	ds_read2st64_b32 v[4:5], v12 offset0:32 offset1:33
	v_max_f32_e32 v3, v168, v168
	s_waitcnt lgkmcnt(0)
	v_max_f32_e32 v2, v4, v4
	v_max_f32_e32 v2, v3, v2
	v_sub_f32_e32 v6, v168, v2
	v_sub_f32_e32 v2, v4, v2
	v_exp_f32_e32 v3, v2
	v_exp_f32_e32 v4, v6
	v_mul_f32_e32 v2, v5, v3
	v_fmac_f32_e32 v2, v0, v4
	v_div_scale_f32 v0, s[14:15], v2, v2, 1.0
	v_rcp_f32_e32 v5, v0
	s_nop 0
	v_fma_f32 v6, -v0, v5, 1.0
	v_fmac_f32_e32 v5, v6, v5
	v_div_scale_f32 v6, vcc, 1.0, v2, 1.0
	v_mul_f32_e32 v7, v6, v5
	v_fma_f32 v8, -v0, v7, v6
	v_fmac_f32_e32 v7, v8, v5
	v_fma_f32 v0, -v0, v7, v6
	v_div_fmas_f32 v0, v0, v5, v7
	v_div_fixup_f32 v11, v0, v2, 1.0
	v_lshlrev_b32_e32 v0, 12, v154
	v_lshl_add_u64 v[6:7], s[12:13], 0, v[0:1]
	s_mov_b64 s[12:13], 0x27388800
	v_lshl_add_u64 v[6:7], v[6:7], 0, s[12:13]
	s_mov_b64 s[12:13], -1
	s_andn2_b64 vcc, exec, s[8:9]
	v_lshlrev_b32_e32 v0, 1, v155
	s_cbranch_vccnz .LBB0_680
	ds_read2st64_b32 v[14:15], v12 offset1:1
	v_mov_b32_e32 v2, v64
	v_lshl_add_u64 v[8:9], v[6:7], 0, v[0:1]
	s_waitcnt lgkmcnt(0)
	ds_read2st64_b32 v[246:247], v12 offset0:2 offset1:3
	v_mov_b32_e32 v5, v14
	v_pk_mul_f32 v[80:81], v[2:3], v[4:5]
	v_mov_b32_e32 v5, v15
	v_add_f32_e32 v2, v80, v81
	v_mul_f32_e32 v13, v11, v2
	v_mov_b32_e32 v2, v65
	v_pk_mul_f32 v[14:15], v[2:3], v[4:5]
	s_nop 0
	v_add_f32_e32 v2, v14, v15
	v_mul_f32_e32 v80, v11, v2
	v_mov_b32_e32 v2, v66
	s_waitcnt lgkmcnt(0)
	ds_read2st64_b32 v[14:15], v12 offset0:4 offset1:5
	v_mov_b32_e32 v5, v246
	v_pk_mul_f32 v[64:65], v[2:3], v[4:5]
	v_mov_b32_e32 v5, v247
	v_add_f32_e32 v2, v64, v65
	v_mul_f32_e32 v64, v11, v2
	v_mov_b32_e32 v2, v67
	v_pk_mul_f32 v[246:247], v[2:3], v[4:5]
	s_nop 0
	v_add_f32_e32 v2, v246, v247
	v_mul_f32_e32 v2, v11, v2
	v_cvt_pk_bf16_f32 v232, v13, v80
	v_cvt_pk_bf16_f32 v233, v64, v2
	v_bfe_u32 v236, v224, 5, 1
	v_lshlrev_b32_e32 v236, 3, v236
	v_mov_b32_e32 v237, 0
	v_lshl_add_u64 v[8:9], v[8:9], 0, v[236:237]
	v_mov_b32_e32 v2, v68
	s_waitcnt lgkmcnt(0)
	ds_read2st64_b32 v[246:247], v12 offset0:6 offset1:7
	v_mov_b32_e32 v5, v14
	v_pk_mul_f32 v[64:65], v[2:3], v[4:5]
	v_mov_b32_e32 v5, v15
	v_add_f32_e32 v2, v64, v65
	v_mul_f32_e32 v13, v11, v2
	v_mov_b32_e32 v2, v69
	v_pk_mul_f32 v[14:15], v[2:3], v[4:5]
	s_nop 0
	v_add_f32_e32 v2, v14, v15
	v_mul_f32_e32 v66, v11, v2
	v_mov_b32_e32 v2, v70
	s_waitcnt lgkmcnt(0)
; template <int DQ, int TYPE>
; __device__ __forceinline__ void attn_item(PP p, int layer, int b, int h, int qt, char* lds, const int tid_, unsigned* next_ctr, volatile XLAS unsigned* slot) {
;     ...
;         if (kh == 0) A_MERGE(0); else A_MERGE(2);
	ds_read2st64_b32 v[14:15], v12 offset0:8 offset1:9
	v_mov_b32_e32 v5, v246
	v_pk_mul_f32 v[64:65], v[2:3], v[4:5]
	v_mov_b32_e32 v5, v247
	v_add_f32_e32 v2, v64, v65
	v_mul_f32_e32 v64, v11, v2
	v_mov_b32_e32 v2, v71
	v_pk_mul_f32 v[246:247], v[2:3], v[4:5]
	s_nop 0
	v_add_f32_e32 v2, v246, v247
	v_mul_f32_e32 v2, v11, v2
	v_cvt_pk_bf16_f32 v234, v13, v66
	v_cvt_pk_bf16_f32 v235, v64, v2
	s_nop 1
	v_permlane32_swap_b32_e32 v232, v234
	v_permlane32_swap_b32_e32 v233, v235
	global_store_dwordx4 v[8:9], v[232:235], off offset:128
	v_mov_b32_e32 v2, v72
	s_waitcnt lgkmcnt(0)
	ds_read2st64_b32 v[246:247], v12 offset0:10 offset1:11
	v_mov_b32_e32 v5, v14
	v_pk_mul_f32 v[64:65], v[2:3], v[4:5]
	v_mov_b32_e32 v5, v15
	v_add_f32_e32 v2, v64, v65
	v_mul_f32_e32 v13, v11, v2
	v_mov_b32_e32 v2, v73
	v_pk_mul_f32 v[14:15], v[2:3], v[4:5]
	s_nop 0
	v_add_f32_e32 v2, v14, v15
	v_mul_f32_e32 v66, v11, v2
	v_mov_b32_e32 v2, v74
	s_waitcnt lgkmcnt(0)
	ds_read2st64_b32 v[14:15], v12 offset0:12 offset1:13
	v_mov_b32_e32 v5, v246
	v_pk_mul_f32 v[64:65], v[2:3], v[4:5]
	v_mov_b32_e32 v5, v247
	v_add_f32_e32 v2, v64, v65
	v_mul_f32_e32 v64, v11, v2
	v_mov_b32_e32 v2, v75
	v_pk_mul_f32 v[246:247], v[2:3], v[4:5]
	s_nop 0
	v_add_f32_e32 v2, v246, v247
	v_mul_f32_e32 v2, v11, v2
	v_cvt_pk_bf16_f32 v232, v13, v66
	v_cvt_pk_bf16_f32 v233, v64, v2
	v_mov_b32_e32 v2, v76
	s_waitcnt lgkmcnt(0)
	ds_read2st64_b32 v[246:247], v12 offset0:14 offset1:15
	v_mov_b32_e32 v5, v14
	v_pk_mul_f32 v[64:65], v[2:3], v[4:5]
	v_mov_b32_e32 v5, v15
	v_add_f32_e32 v2, v64, v65
	v_mul_f32_e32 v13, v11, v2
	v_mov_b32_e32 v2, v77
	v_pk_mul_f32 v[14:15], v[2:3], v[4:5]
	s_nop 0
	v_add_f32_e32 v2, v14, v15
	v_mul_f32_e32 v66, v11, v2
	v_mov_b32_e32 v2, v78
	s_waitcnt lgkmcnt(0)
	ds_read2st64_b32 v[14:15], v12 offset0:16 offset1:17
	v_mov_b32_e32 v5, v246
	v_pk_mul_f32 v[64:65], v[2:3], v[4:5]
	v_mov_b32_e32 v5, v247
	v_add_f32_e32 v2, v64, v65
	v_mul_f32_e32 v64, v11, v2
	v_mov_b32_e32 v2, v79
	v_pk_mul_f32 v[246:247], v[2:3], v[4:5]
	s_nop 0
	v_add_f32_e32 v2, v246, v247
	v_mul_f32_e32 v2, v11, v2
	v_cvt_pk_bf16_f32 v234, v13, v66
	v_cvt_pk_bf16_f32 v235, v64, v2
	s_nop 1
	v_permlane32_swap_b32_e32 v232, v234
	v_permlane32_swap_b32_e32 v233, v235
	global_store_dwordx4 v[8:9], v[232:235], off offset:160
	v_mov_b32_e32 v2, v48
	s_waitcnt lgkmcnt(0)
	ds_read2st64_b32 v[246:247], v12 offset0:18 offset1:19
	v_mov_b32_e32 v5, v14
	v_pk_mul_f32 v[64:65], v[2:3], v[4:5]
	v_mov_b32_e32 v5, v15
	v_add_f32_e32 v2, v64, v65
	v_mul_f32_e32 v13, v11, v2
	v_mov_b32_e32 v2, v49
	v_pk_mul_f32 v[14:15], v[2:3], v[4:5]
	s_nop 0
	v_add_f32_e32 v2, v14, v15
	v_mul_f32_e32 v64, v11, v2
	v_mov_b32_e32 v2, v50
	s_waitcnt lgkmcnt(0)
	ds_read2st64_b32 v[14:15], v12 offset0:20 offset1:21
	v_mov_b32_e32 v5, v246
	v_pk_mul_f32 v[48:49], v[2:3], v[4:5]
	v_mov_b32_e32 v5, v247
	v_add_f32_e32 v2, v48, v49
	v_mul_f32_e32 v48, v11, v2
	v_mov_b32_e32 v2, v51
	v_pk_mul_f32 v[246:247], v[2:3], v[4:5]
	s_nop 0
	v_add_f32_e32 v2, v246, v247
	v_mul_f32_e32 v2, v11, v2
	v_cvt_pk_bf16_f32 v232, v13, v64
	v_cvt_pk_bf16_f32 v233, v48, v2
	v_mov_b32_e32 v2, v52
	s_waitcnt lgkmcnt(0)
	ds_read2st64_b32 v[246:247], v12 offset0:22 offset1:23
	v_mov_b32_e32 v5, v14
	v_pk_mul_f32 v[48:49], v[2:3], v[4:5]
	v_mov_b32_e32 v5, v15
	v_add_f32_e32 v2, v48, v49
	v_mul_f32_e32 v13, v11, v2
	v_mov_b32_e32 v2, v53
	v_pk_mul_f32 v[14:15], v[2:3], v[4:5]
	s_nop 0
	v_add_f32_e32 v2, v14, v15
	v_mul_f32_e32 v50, v11, v2
	v_mov_b32_e32 v2, v54
	s_waitcnt lgkmcnt(0)
	ds_read2st64_b32 v[14:15], v12 offset0:24 offset1:25
	v_mov_b32_e32 v5, v246
	v_pk_mul_f32 v[48:49], v[2:3], v[4:5]
	v_mov_b32_e32 v5, v247
	v_add_f32_e32 v2, v48, v49
	v_mul_f32_e32 v48, v11, v2
	v_mov_b32_e32 v2, v55
	v_pk_mul_f32 v[246:247], v[2:3], v[4:5]
	s_nop 0
	v_add_f32_e32 v2, v246, v247
	v_mul_f32_e32 v2, v11, v2
	v_cvt_pk_bf16_f32 v234, v13, v50
	v_cvt_pk_bf16_f32 v235, v48, v2
	s_nop 1
	v_permlane32_swap_b32_e32 v232, v234
	v_permlane32_swap_b32_e32 v233, v235
	global_store_dwordx4 v[8:9], v[232:235], off offset:192
	v_mov_b32_e32 v2, v56
	s_waitcnt lgkmcnt(0)
	ds_read2st64_b32 v[246:247], v12 offset0:26 offset1:27
	v_mov_b32_e32 v5, v14
	v_pk_mul_f32 v[48:49], v[2:3], v[4:5]
	v_mov_b32_e32 v5, v15
	v_add_f32_e32 v2, v48, v49
	v_mul_f32_e32 v13, v11, v2
	v_mov_b32_e32 v2, v57
	v_pk_mul_f32 v[14:15], v[2:3], v[4:5]
	s_nop 0
	v_add_f32_e32 v2, v14, v15
	v_mul_f32_e32 v50, v11, v2
	v_mov_b32_e32 v2, v58
	s_waitcnt lgkmcnt(0)
	ds_read2st64_b32 v[14:15], v12 offset0:28 offset1:29
	v_mov_b32_e32 v5, v246
	v_pk_mul_f32 v[48:49], v[2:3], v[4:5]
	v_mov_b32_e32 v5, v247
	v_add_f32_e32 v2, v48, v49
	v_mul_f32_e32 v48, v11, v2
	v_mov_b32_e32 v2, v59
	v_pk_mul_f32 v[246:247], v[2:3], v[4:5]
	s_nop 0
	v_add_f32_e32 v2, v246, v247
	v_mul_f32_e32 v2, v11, v2
	v_cvt_pk_bf16_f32 v232, v13, v50
	v_cvt_pk_bf16_f32 v233, v48, v2
	v_mov_b32_e32 v2, v60
	s_waitcnt lgkmcnt(0)
	ds_read2st64_b32 v[246:247], v12 offset0:30 offset1:31
	v_mov_b32_e32 v5, v14
	v_pk_mul_f32 v[48:49], v[2:3], v[4:5]
	v_mov_b32_e32 v5, v15
	v_add_f32_e32 v2, v48, v49
	v_mul_f32_e32 v13, v11, v2
	v_mov_b32_e32 v2, v61
	v_pk_mul_f32 v[14:15], v[2:3], v[4:5]
	s_nop 0
	v_add_f32_e32 v2, v14, v15
	v_mul_f32_e32 v50, v11, v2
	v_mov_b32_e32 v2, v62
	s_waitcnt lgkmcnt(0)
	v_mov_b32_e32 v5, v246
	v_pk_mul_f32 v[48:49], v[2:3], v[4:5]
	v_mov_b32_e32 v5, v247
	v_add_f32_e32 v2, v48, v49
	v_mul_f32_e32 v48, v11, v2
	v_mov_b32_e32 v2, v63
	v_pk_mul_f32 v[246:247], v[2:3], v[4:5]
	s_nop 0
	v_add_f32_e32 v2, v246, v247
	v_mul_f32_e32 v2, v11, v2
	v_cvt_pk_bf16_f32 v234, v13, v50
	v_cvt_pk_bf16_f32 v235, v48, v2
	s_nop 1
	v_permlane32_swap_b32_e32 v232, v234
	v_permlane32_swap_b32_e32 v233, v235
	global_store_dwordx4 v[8:9], v[232:235], off offset:224
	s_cbranch_execz .LBB0_681

; __device__ __forceinline__ float fast_exp2(float x) { return __builtin_amdgcn_exp2f(x); }
; template <int DQ, int TYPE>
; __device__ __forceinline__ void attn_item(PP p, int layer, int b, int h, int qt, char* lds, const int tid_, unsigned* next_ctr, volatile XLAS unsigned* slot) {
;     ...
;     l_run += __shfl_xor(l_run, 32);
;     float* mrg = (float*)lds;
;     {
;         float* mp = mrg + (size_t)((qg * 2 + kh) * 34) * 64 + lane;
;         if (kh == 0) {
; #pragma unroll
;             for (int t2 = 0; t2 < 2; ++t2)
; #pragma unroll
;                 for (int i = 0; i < 16; ++i) mp[(t2 * 16 + i) * 64] = O[2 + t2][i];
;         } else {
; #pragma unroll
;             for (int t2 = 0; t2 < 2; ++t2)
; #pragma unroll
;                 for (int i = 0; i < 16; ++i) mp[(t2 * 16 + i) * 64] = O[t2][i];
;         }
;         mp[32 * 64] = m_run; mp[33 * 64] = l_run;
;     }
;     __syncthreads();
;     {
;         const float* mp = mrg + (size_t)((qg * 2 + (kh ^ 1)) * 34) * 64 + lane;
;         const float m1 = mp[32 * 64], l1 = mp[33 * 64];
;         const float mt = fmaxf(m_run, m1);
;         const float a0 = fast_exp2(m_run - mt), a1 = fast_exp2(m1 - mt);
;         const float inv = 1.0f / (l_run * a0 + l1 * a1);
;         bf16_t* orow = Op + (size_t)qpos * D;
;     ...
;         if (kh == 0) A_MERGE(0); else A_MERGE(2);
.LBB0_653:
	s_or_b64 exec, exec, s[12:13]
	s_load_dwordx2 s[14:15], s[0:1], 0x98
	s_lshl_b32 s12, s56, 12
	v_and_b32_e32 v67, 64, v224
	v_xor_b32_e32 v66, 32, v224
	v_add_u32_e32 v67, 64, v67
	s_waitcnt lgkmcnt(0)
	s_add_u32 s12, s14, s12
	s_addc_u32 s13, s15, 0
	s_lshl_b32 s14, s55, 1
	s_add_u32 s12, s12, s14
	v_cmp_lt_i32_e32 vcc, v66, v67
	s_addc_u32 s13, s13, 0
	s_lshl_b32 s14, s81, 1
	v_cndmask_b32_e32 v66, v224, v66, vcc
	s_add_i32 s15, s14, s54
	v_lshlrev_b32_e32 v66, 2, v66
	s_mulk_i32 s15, 0x2200
	ds_bpermute_b32 v66, v66, v164
	s_add_i32 s15, s15, 16
	v_lshlrev_b32_e32 v67, 2, v183
	v_add_u32_e32 v68, s15, v67
	s_xor_b32 s15, s54, 1
	s_add_i32 s14, s14, s15
	s_mulk_i32 s14, 0x2200
	v_cndmask_b32_e64 v76, v27, v59, s[52:53]
	s_waitcnt vmcnt(3)
	v_cndmask_b32_e64 v84, v19, v51, s[52:53]
	v_cndmask_b32_e64 v85, v18, v50, s[52:53]
	s_add_i32 s14, s14, 16
	s_waitcnt lgkmcnt(0)
	v_add_f32_e32 v66, v164, v66
	v_cndmask_b32_e64 v69, v33, v65, s[52:53]
	v_cndmask_b32_e64 v70, v32, v64, s[52:53]
	v_cndmask_b32_e64 v71, v31, v63, s[52:53]
	v_cndmask_b32_e64 v72, v30, v62, s[52:53]
	v_cndmask_b32_e64 v73, v29, v61, s[52:53]
	v_cndmask_b32_e64 v75, v28, v60, s[52:53]
	v_cndmask_b32_e64 v77, v26, v58, s[52:53]
	v_cndmask_b32_e64 v78, v25, v57, s[52:53]
	v_cndmask_b32_e64 v79, v24, v56, s[52:53]
	v_cndmask_b32_e64 v80, v23, v55, s[52:53]
	v_cndmask_b32_e64 v81, v22, v54, s[52:53]
	v_cndmask_b32_e64 v82, v21, v53, s[52:53]
	v_cndmask_b32_e64 v83, v20, v52, s[52:53]
	s_waitcnt vmcnt(2)
	v_cndmask_b32_e64 v86, v17, v49, s[52:53]
	v_cndmask_b32_e64 v87, v16, v48, s[52:53]
	v_cndmask_b32_e64 v88, v15, v47, s[52:53]
	v_cndmask_b32_e64 v89, v14, v46, s[52:53]
	v_cndmask_b32_e64 v90, v13, v45, s[52:53]
	v_cndmask_b32_e64 v91, v12, v44, s[52:53]
	v_cndmask_b32_e64 v92, v11, v43, s[52:53]
	v_cndmask_b32_e64 v93, v10, v42, s[52:53]
	v_cndmask_b32_e64 v94, v9, v41, s[52:53]
	v_cndmask_b32_e64 v95, v8, v40, s[52:53]
	v_cndmask_b32_e64 v96, v7, v39, s[52:53]
	v_cndmask_b32_e64 v97, v6, v38, s[52:53]
	v_cndmask_b32_e64 v98, v5, v37, s[52:53]
	v_cndmask_b32_e64 v99, v4, v36, s[52:53]
	v_cndmask_b32_e64 v100, v3, v35, s[52:53]
	v_cndmask_b32_e64 v101, v2, v34, s[52:53]
	ds_write2st64_b32 v68, v85, v84 offset1:1
	ds_write2st64_b32 v68, v83, v82 offset0:2 offset1:3
	ds_write2st64_b32 v68, v81, v80 offset0:4 offset1:5
	ds_write2st64_b32 v68, v79, v78 offset0:6 offset1:7
	ds_write2st64_b32 v68, v77, v76 offset0:8 offset1:9
	ds_write2st64_b32 v68, v75, v73 offset0:10 offset1:11
	ds_write2st64_b32 v68, v72, v71 offset0:12 offset1:13
	ds_write2st64_b32 v68, v70, v69 offset0:14 offset1:15
	ds_write2st64_b32 v68, v101, v100 offset0:16 offset1:17
	ds_write2st64_b32 v68, v99, v98 offset0:18 offset1:19
	ds_write2st64_b32 v68, v97, v96 offset0:20 offset1:21
	ds_write2st64_b32 v68, v95, v94 offset0:22 offset1:23
	ds_write2st64_b32 v68, v93, v92 offset0:24 offset1:25
	ds_write2st64_b32 v68, v91, v90 offset0:26 offset1:27
	ds_write2st64_b32 v68, v89, v88 offset0:28 offset1:29
	ds_write2st64_b32 v68, v87, v86 offset0:30 offset1:31
	ds_write2st64_b32 v68, v165, v66 offset0:32 offset1:33
	v_add_u32_e32 v76, s14, v67
	s_waitcnt lgkmcnt(0)
	s_barrier
	ds_read2st64_b32 v[68:69], v76 offset0:32 offset1:33
	v_max_f32_e32 v70, v165, v165
	s_waitcnt lgkmcnt(0)
	v_max_f32_e32 v67, v68, v68
	v_max_f32_e32 v67, v70, v67
	v_sub_f32_e32 v70, v165, v67
	v_sub_f32_e32 v67, v68, v67
	v_exp_f32_e32 v67, v67
	v_exp_f32_e32 v68, v70
	v_mul_f32_e32 v69, v69, v67
	v_fmac_f32_e32 v69, v66, v68
	v_div_scale_f32 v66, s[14:15], v69, v69, 1.0
	v_rcp_f32_e32 v70, v66
	s_nop 0
	v_fma_f32 v71, -v66, v70, 1.0
	v_fmac_f32_e32 v70, v71, v70
	v_div_scale_f32 v71, vcc, 1.0, v69, 1.0
	v_mul_f32_e32 v72, v71, v70
	v_fma_f32 v73, -v66, v72, v71
	v_fmac_f32_e32 v72, v73, v70
	v_fma_f32 v66, -v66, v72, v71
	v_div_fmas_f32 v66, v66, v70, v72
	v_lshlrev_b64 v[70:71], 12, v[0:1]
	v_lshl_add_u64 v[70:71], s[12:13], 0, v[70:71]
	s_mov_b64 s[12:13], 0x27388400
	v_div_fixup_f32 v75, v66, v69, 1.0
	v_lshl_add_u64 v[70:71], v[70:71], 0, s[12:13]
	s_mov_b64 s[12:13], -1
	s_andn2_b64 vcc, exec, s[8:9]
	v_lshlrev_b32_e32 v0, 1, v147
	s_cbranch_vccnz .LBB0_682
	ds_read2st64_b32 v[78:79], v76 offset1:1
	v_mov_b32_e32 v66, v50
	v_lshl_add_u64 v[72:73], v[70:71], 0, v[0:1]
	s_waitcnt lgkmcnt(0)
	v_mov_b32_e32 v69, v78
	v_pk_mul_f32 v[80:81], v[66:67], v[68:69]
	v_mov_b32_e32 v66, v51
	v_add_f32_e32 v50, v80, v81
	v_mov_b32_e32 v69, v79
	v_mul_f32_e32 v77, v75, v50
	v_pk_mul_f32 v[50:51], v[66:67], v[68:69]
	v_mov_b32_e32 v66, v52
	v_add_f32_e32 v50, v50, v51
	v_mul_f32_e32 v80, v75, v50
	ds_read2st64_b32 v[50:51], v76 offset0:2 offset1:3
	s_waitcnt lgkmcnt(0)
	ds_read2st64_b32 v[246:247], v76 offset0:4 offset1:5
	v_mov_b32_e32 v69, v50
	v_pk_mul_f32 v[78:79], v[66:67], v[68:69]
	v_mov_b32_e32 v66, v53
	v_add_f32_e32 v50, v78, v79
	v_mov_b32_e32 v69, v51
	v_mul_f32_e32 v52, v75, v50
	v_pk_mul_f32 v[50:51], v[66:67], v[68:69]
	v_mov_b32_e32 v66, v54
	v_add_f32_e32 v50, v50, v51
	v_mul_f32_e32 v51, v75, v50
	v_cvt_pk_bf16_f32 v232, v77, v80
	v_cvt_pk_bf16_f32 v233, v52, v51
	v_bfe_u32 v236, v224, 5, 1
	v_lshlrev_b32_e32 v236, 3, v236
	v_mov_b32_e32 v237, 0
	v_lshl_add_u64 v[72:73], v[72:73], 0, v[236:237]
	s_waitcnt lgkmcnt(0)
	ds_read2st64_b32 v[50:51], v76 offset0:6 offset1:7
	v_mov_b32_e32 v69, v246
	v_pk_mul_f32 v[52:53], v[66:67], v[68:69]
	v_mov_b32_e32 v66, v55
	v_add_f32_e32 v246, v52, v53
	v_mov_b32_e32 v69, v247
	v_mul_f32_e32 v54, v75, v246
	v_pk_mul_f32 v[246:247], v[66:67], v[68:69]
	v_mov_b32_e32 v66, v56
	v_add_f32_e32 v246, v246, v247
	v_mul_f32_e32 v55, v75, v246
	s_waitcnt lgkmcnt(0)
; template <int DQ, int TYPE>
; __device__ __forceinline__ void attn_item(PP p, int layer, int b, int h, int qt, char* lds, const int tid_, unsigned* next_ctr, volatile XLAS unsigned* slot) {
;     ...
;         if (kh == 0) A_MERGE(0); else A_MERGE(2);
	ds_read2st64_b32 v[246:247], v76 offset0:8 offset1:9
	v_mov_b32_e32 v69, v50
	v_pk_mul_f32 v[52:53], v[66:67], v[68:69]
	v_mov_b32_e32 v66, v57
	v_add_f32_e32 v50, v52, v53
	v_mov_b32_e32 v69, v51
	v_mul_f32_e32 v52, v75, v50
	v_pk_mul_f32 v[50:51], v[66:67], v[68:69]
	v_mov_b32_e32 v66, v58
	v_add_f32_e32 v50, v50, v51
	v_mul_f32_e32 v51, v75, v50
	v_cvt_pk_bf16_f32 v234, v54, v55
	v_cvt_pk_bf16_f32 v235, v52, v51
	s_nop 1
	v_permlane32_swap_b32_e32 v232, v234
	v_permlane32_swap_b32_e32 v233, v235
	global_store_dwordx4 v[72:73], v[232:235], off offset:128
	s_waitcnt lgkmcnt(0)
	ds_read2st64_b32 v[50:51], v76 offset0:10 offset1:11
	v_mov_b32_e32 v69, v246
	v_pk_mul_f32 v[52:53], v[66:67], v[68:69]
	v_mov_b32_e32 v66, v59
	v_add_f32_e32 v246, v52, v53
	v_mov_b32_e32 v69, v247
	v_mul_f32_e32 v54, v75, v246
	v_pk_mul_f32 v[246:247], v[66:67], v[68:69]
	v_mov_b32_e32 v66, v60
	v_add_f32_e32 v246, v246, v247
	v_mul_f32_e32 v55, v75, v246
	s_waitcnt lgkmcnt(0)
	ds_read2st64_b32 v[246:247], v76 offset0:12 offset1:13
	v_mov_b32_e32 v69, v50
	v_pk_mul_f32 v[52:53], v[66:67], v[68:69]
	v_mov_b32_e32 v66, v61
	v_add_f32_e32 v50, v52, v53
	v_mov_b32_e32 v69, v51
	v_mul_f32_e32 v52, v75, v50
	v_pk_mul_f32 v[50:51], v[66:67], v[68:69]
	v_mov_b32_e32 v66, v62
	v_add_f32_e32 v50, v50, v51
	v_mul_f32_e32 v51, v75, v50
	v_cvt_pk_bf16_f32 v232, v54, v55
	v_cvt_pk_bf16_f32 v233, v52, v51
	s_waitcnt lgkmcnt(0)
	ds_read2st64_b32 v[50:51], v76 offset0:14 offset1:15
	v_mov_b32_e32 v69, v246
	v_pk_mul_f32 v[52:53], v[66:67], v[68:69]
	v_mov_b32_e32 v66, v63
	v_add_f32_e32 v246, v52, v53
	v_mov_b32_e32 v69, v247
	v_mul_f32_e32 v54, v75, v246
	v_pk_mul_f32 v[246:247], v[66:67], v[68:69]
	v_mov_b32_e32 v66, v64
	v_add_f32_e32 v246, v246, v247
	v_mul_f32_e32 v55, v75, v246
	s_waitcnt lgkmcnt(0)
	ds_read2st64_b32 v[246:247], v76 offset0:16 offset1:17
	v_mov_b32_e32 v69, v50
	v_pk_mul_f32 v[52:53], v[66:67], v[68:69]
	v_mov_b32_e32 v66, v65
	v_add_f32_e32 v50, v52, v53
	v_mov_b32_e32 v69, v51
	v_mul_f32_e32 v52, v75, v50
	v_pk_mul_f32 v[50:51], v[66:67], v[68:69]
	v_mov_b32_e32 v66, v34
	v_add_f32_e32 v50, v50, v51
	v_mul_f32_e32 v51, v75, v50
	v_cvt_pk_bf16_f32 v234, v54, v55
	v_cvt_pk_bf16_f32 v235, v52, v51
	s_nop 1
	v_permlane32_swap_b32_e32 v232, v234
	v_permlane32_swap_b32_e32 v233, v235
	global_store_dwordx4 v[72:73], v[232:235], off offset:160
	s_waitcnt lgkmcnt(0)
	v_mov_b32_e32 v69, v246
	v_pk_mul_f32 v[52:53], v[66:67], v[68:69]
	v_mov_b32_e32 v66, v35
	v_add_f32_e32 v34, v52, v53
	v_mov_b32_e32 v69, v247
	v_mul_f32_e32 v52, v75, v34
	v_pk_mul_f32 v[34:35], v[66:67], v[68:69]
	v_mov_b32_e32 v66, v36
	v_add_f32_e32 v34, v34, v35
	v_mul_f32_e32 v53, v75, v34
	ds_read2st64_b32 v[34:35], v76 offset0:18 offset1:19
	s_waitcnt lgkmcnt(0)
	ds_read2st64_b32 v[246:247], v76 offset0:20 offset1:21
	v_mov_b32_e32 v69, v34
	v_pk_mul_f32 v[50:51], v[66:67], v[68:69]
	v_mov_b32_e32 v66, v37
	v_add_f32_e32 v34, v50, v51
	v_mov_b32_e32 v69, v35
	v_mul_f32_e32 v36, v75, v34
	v_pk_mul_f32 v[34:35], v[66:67], v[68:69]
	v_mov_b32_e32 v66, v38
	v_add_f32_e32 v34, v34, v35
	v_mul_f32_e32 v35, v75, v34
	v_cvt_pk_bf16_f32 v232, v52, v53
	v_cvt_pk_bf16_f32 v233, v36, v35
	s_waitcnt lgkmcnt(0)
	ds_read2st64_b32 v[34:35], v76 offset0:22 offset1:23
	v_mov_b32_e32 v69, v246
	v_pk_mul_f32 v[36:37], v[66:67], v[68:69]
	v_mov_b32_e32 v66, v39
	v_add_f32_e32 v246, v36, v37
	v_mov_b32_e32 v69, v247
	v_mul_f32_e32 v38, v75, v246
	v_pk_mul_f32 v[246:247], v[66:67], v[68:69]
	v_mov_b32_e32 v66, v40
	v_add_f32_e32 v246, v246, v247
	v_mul_f32_e32 v39, v75, v246
	s_waitcnt lgkmcnt(0)
	ds_read2st64_b32 v[246:247], v76 offset0:24 offset1:25
	v_mov_b32_e32 v69, v34
	v_pk_mul_f32 v[36:37], v[66:67], v[68:69]
	v_mov_b32_e32 v66, v41
	v_add_f32_e32 v34, v36, v37
	v_mov_b32_e32 v69, v35
	v_mul_f32_e32 v36, v75, v34
	v_pk_mul_f32 v[34:35], v[66:67], v[68:69]
	v_mov_b32_e32 v66, v42
	v_add_f32_e32 v34, v34, v35
	v_mul_f32_e32 v35, v75, v34
	v_cvt_pk_bf16_f32 v234, v38, v39
	v_cvt_pk_bf16_f32 v235, v36, v35
	s_nop 1
	v_permlane32_swap_b32_e32 v232, v234
	v_permlane32_swap_b32_e32 v233, v235
	global_store_dwordx4 v[72:73], v[232:235], off offset:192
	s_waitcnt lgkmcnt(0)
	ds_read2st64_b32 v[34:35], v76 offset0:26 offset1:27
	v_mov_b32_e32 v69, v246
	v_pk_mul_f32 v[36:37], v[66:67], v[68:69]
	v_mov_b32_e32 v66, v43
	v_add_f32_e32 v246, v36, v37
	v_mov_b32_e32 v69, v247
	v_mul_f32_e32 v38, v75, v246
	v_pk_mul_f32 v[246:247], v[66:67], v[68:69]
	v_mov_b32_e32 v66, v44
	v_add_f32_e32 v246, v246, v247
	v_mul_f32_e32 v39, v75, v246
	s_waitcnt lgkmcnt(0)
	ds_read2st64_b32 v[246:247], v76 offset0:28 offset1:29
	v_mov_b32_e32 v69, v34
	v_pk_mul_f32 v[36:37], v[66:67], v[68:69]
	v_mov_b32_e32 v66, v45
	v_add_f32_e32 v34, v36, v37
	v_mov_b32_e32 v69, v35
	v_mul_f32_e32 v36, v75, v34
	v_pk_mul_f32 v[34:35], v[66:67], v[68:69]
	v_mov_b32_e32 v66, v46
	v_add_f32_e32 v34, v34, v35
	v_mul_f32_e32 v35, v75, v34
	v_cvt_pk_bf16_f32 v232, v38, v39
	v_cvt_pk_bf16_f32 v233, v36, v35
	s_waitcnt lgkmcnt(0)
	ds_read2st64_b32 v[34:35], v76 offset0:30 offset1:31
	v_mov_b32_e32 v69, v246
	v_pk_mul_f32 v[36:37], v[66:67], v[68:69]
	v_mov_b32_e32 v66, v47
	v_add_f32_e32 v246, v36, v37
	v_mov_b32_e32 v69, v247
	v_mul_f32_e32 v38, v75, v246
	v_pk_mul_f32 v[246:247], v[66:67], v[68:69]
	v_mov_b32_e32 v66, v48
	v_add_f32_e32 v246, v246, v247
	v_mul_f32_e32 v39, v75, v246
	s_waitcnt lgkmcnt(0)
	v_mov_b32_e32 v69, v34
	v_pk_mul_f32 v[36:37], v[66:67], v[68:69]
	v_mov_b32_e32 v66, v49
	v_add_f32_e32 v34, v36, v37
	v_mov_b32_e32 v69, v35
	v_mul_f32_e32 v36, v75, v34
	v_pk_mul_f32 v[34:35], v[66:67], v[68:69]
	s_nop 0
	v_add_f32_e32 v34, v34, v35
	v_mul_f32_e32 v35, v75, v34
	v_cvt_pk_bf16_f32 v234, v38, v39
	v_cvt_pk_bf16_f32 v235, v36, v35
	s_nop 1
	v_permlane32_swap_b32_e32 v232, v234
	v_permlane32_swap_b32_e32 v233, v235
	global_store_dwordx4 v[72:73], v[232:235], off offset:224
	s_cbranch_execz .LBB0_683

; __device__ __forceinline__ float fast_exp2(float x) { return __builtin_amdgcn_exp2f(x); }
; template <int DQ, int TYPE>
; __device__ __forceinline__ void attn_item(PP p, int layer, int b, int h, int qt, char* lds, const int tid_, unsigned* next_ctr, volatile XLAS unsigned* slot) {
;     ...
;     l_run += __shfl_xor(l_run, 32);
;     float* mrg = (float*)lds;
;     {
;         float* mp = mrg + (size_t)((qg * 2 + kh) * 34) * 64 + lane;
;         if (kh == 0) {
; #pragma unroll
;             for (int t2 = 0; t2 < 2; ++t2)
; #pragma unroll
;                 for (int i = 0; i < 16; ++i) mp[(t2 * 16 + i) * 64] = O[2 + t2][i];
;         } else {
; #pragma unroll
;             for (int t2 = 0; t2 < 2; ++t2)
; #pragma unroll
;                 for (int i = 0; i < 16; ++i) mp[(t2 * 16 + i) * 64] = O[t2][i];
;         }
;         mp[32 * 64] = m_run; mp[33 * 64] = l_run;
;     }
;     __syncthreads();
;     {
;         const float* mp = mrg + (size_t)((qg * 2 + (kh ^ 1)) * 34) * 64 + lane;
;         const float m1 = mp[32 * 64], l1 = mp[33 * 64];
;         const float mt = fmaxf(m_run, m1);
;         const float a0 = fast_exp2(m_run - mt), a1 = fast_exp2(m1 - mt);
;         const float inv = 1.0f / (l_run * a0 + l1 * a1);
;         bf16_t* orow = Op + (size_t)qpos * D;
;     ...
;         if (kh == 0) A_MERGE(0); else A_MERGE(2);
.LBB0_677:
	s_or_b64 exec, exec, s[12:13]
	s_lshl_b32 s12, s55, 12
	s_add_u32 s12, s38, s12
	v_and_b32_e32 v66, 64, v224
	s_addc_u32 s13, s39, 0
	s_lshl_b32 s14, s54, 8
	v_xor_b32_e32 v0, 32, v224
	v_add_u32_e32 v66, 64, v66
	s_add_u32 s12, s12, s14
	v_cmp_lt_i32_e32 vcc, v0, v66
	s_addc_u32 s13, s13, 0
	s_lshl_b32 s14, s48, 1
	v_cndmask_b32_e32 v0, v224, v0, vcc
	s_add_i32 s15, s14, s56
	v_lshlrev_b32_e32 v0, 2, v0
	s_mulk_i32 s15, 0x2200
	ds_bpermute_b32 v0, v0, v199
	s_add_i32 s15, s15, 16
	v_lshlrev_b32_e32 v66, 2, v183
	v_add_u32_e32 v67, s15, v66
	s_xor_b32 s15, s56, 1
	s_add_i32 s14, s14, s15
	s_mulk_i32 s14, 0x2200
	v_cndmask_b32_e64 v76, v26, v58, s[52:53]
	v_cndmask_b32_e64 v83, v19, v51, s[52:53]
	v_cndmask_b32_e64 v84, v18, v50, s[52:53]
	s_add_i32 s14, s14, 16
	s_waitcnt lgkmcnt(0)
	v_add_f32_e32 v0, v199, v0
	v_cndmask_b32_e64 v68, v33, v65, s[52:53]
	v_cndmask_b32_e64 v69, v32, v64, s[52:53]
	v_cndmask_b32_e64 v70, v31, v63, s[52:53]
	v_cndmask_b32_e64 v71, v30, v62, s[52:53]
	v_cndmask_b32_e64 v72, v29, v61, s[52:53]
	v_cndmask_b32_e64 v73, v28, v60, s[52:53]
	v_cndmask_b32_e64 v75, v27, v59, s[52:53]
	v_cndmask_b32_e64 v77, v25, v57, s[52:53]
	v_cndmask_b32_e64 v78, v24, v56, s[52:53]
	v_cndmask_b32_e64 v79, v23, v55, s[52:53]
	v_cndmask_b32_e64 v80, v22, v54, s[52:53]
	v_cndmask_b32_e64 v81, v21, v53, s[52:53]
	v_cndmask_b32_e64 v82, v20, v52, s[52:53]
	v_cndmask_b32_e64 v85, v17, v49, s[52:53]
	s_waitcnt vmcnt(4)
	v_cndmask_b32_e64 v86, v16, v48, s[52:53]
	v_cndmask_b32_e64 v87, v15, v47, s[52:53]
	v_cndmask_b32_e64 v88, v14, v46, s[52:53]
	v_cndmask_b32_e64 v89, v13, v45, s[52:53]
	s_waitcnt vmcnt(3)
	v_cndmask_b32_e64 v90, v12, v44, s[52:53]
	v_cndmask_b32_e64 v91, v11, v43, s[52:53]
	v_cndmask_b32_e64 v92, v10, v42, s[52:53]
	v_cndmask_b32_e64 v93, v9, v41, s[52:53]
	v_cndmask_b32_e64 v94, v8, v40, s[52:53]
	v_cndmask_b32_e64 v95, v7, v39, s[52:53]
	v_cndmask_b32_e64 v96, v6, v38, s[52:53]
	v_cndmask_b32_e64 v97, v5, v37, s[52:53]
	v_cndmask_b32_e64 v98, v4, v36, s[52:53]
	v_cndmask_b32_e64 v99, v3, v35, s[52:53]
	v_cndmask_b32_e64 v100, v2, v34, s[52:53]
	ds_write2st64_b32 v67, v84, v83 offset1:1
	ds_write2st64_b32 v67, v82, v81 offset0:2 offset1:3
	ds_write2st64_b32 v67, v80, v79 offset0:4 offset1:5
	ds_write2st64_b32 v67, v78, v77 offset0:6 offset1:7
	ds_write2st64_b32 v67, v76, v75 offset0:8 offset1:9
	ds_write2st64_b32 v67, v73, v72 offset0:10 offset1:11
	ds_write2st64_b32 v67, v71, v70 offset0:12 offset1:13
	ds_write2st64_b32 v67, v69, v68 offset0:14 offset1:15
	ds_write2st64_b32 v67, v100, v99 offset0:16 offset1:17
	ds_write2st64_b32 v67, v98, v97 offset0:18 offset1:19
	ds_write2st64_b32 v67, v96, v95 offset0:20 offset1:21
	ds_write2st64_b32 v67, v94, v93 offset0:22 offset1:23
	ds_write2st64_b32 v67, v92, v91 offset0:24 offset1:25
	ds_write2st64_b32 v67, v90, v89 offset0:26 offset1:27
	ds_write2st64_b32 v67, v88, v87 offset0:28 offset1:29
	ds_write2st64_b32 v67, v86, v85 offset0:30 offset1:31
	ds_write2st64_b32 v67, v200, v0 offset0:32 offset1:33
	v_add_u32_e32 v76, s14, v66
	s_waitcnt lgkmcnt(0)
	s_barrier
	ds_read2st64_b32 v[68:69], v76 offset0:32 offset1:33
	v_max_f32_e32 v67, v200, v200
	s_waitcnt lgkmcnt(0)
	v_max_f32_e32 v66, v68, v68
	v_max_f32_e32 v66, v67, v66
	v_sub_f32_e32 v70, v200, v66
	v_sub_f32_e32 v66, v68, v66
	v_exp_f32_e32 v67, v66
	v_exp_f32_e32 v68, v70
	v_mul_f32_e32 v66, v69, v67
	v_fmac_f32_e32 v66, v0, v68
	v_div_scale_f32 v0, s[14:15], v66, v66, 1.0
	v_rcp_f32_e32 v69, v0
	s_nop 0
	v_fma_f32 v70, -v0, v69, 1.0
	v_fmac_f32_e32 v69, v70, v69
	v_div_scale_f32 v70, vcc, 1.0, v66, 1.0
	v_mul_f32_e32 v71, v70, v69
	v_fma_f32 v72, -v0, v71, v70
	v_fmac_f32_e32 v71, v72, v69
	v_fma_f32 v0, -v0, v71, v70
	v_div_fmas_f32 v0, v0, v69, v71
	v_lshlrev_b64 v[70:71], 12, v[172:173]
	v_div_fixup_f32 v75, v0, v66, 1.0
	v_lshl_add_u64 v[70:71], s[12:13], 0, v[70:71]
	s_mov_b64 s[12:13], -1
	s_andn2_b64 vcc, exec, s[8:9]
	v_lshlrev_b32_e32 v0, 1, v187
	s_cbranch_vccnz .LBB0_684
	ds_read2st64_b32 v[78:79], v76 offset1:1
	v_mov_b32_e32 v66, v50
	v_lshl_add_u64 v[72:73], v[70:71], 0, v[0:1]
	s_waitcnt lgkmcnt(0)
	v_mov_b32_e32 v69, v78
	v_pk_mul_f32 v[80:81], v[66:67], v[68:69]
	v_mov_b32_e32 v66, v51
	v_add_f32_e32 v50, v80, v81
	v_mov_b32_e32 v69, v79
	v_mul_f32_e32 v77, v75, v50
	v_pk_mul_f32 v[50:51], v[66:67], v[68:69]
	v_mov_b32_e32 v66, v52
	v_add_f32_e32 v50, v50, v51
	v_mul_f32_e32 v80, v75, v50
	ds_read2st64_b32 v[50:51], v76 offset0:2 offset1:3
	s_waitcnt lgkmcnt(0)
	ds_read2st64_b32 v[246:247], v76 offset0:4 offset1:5
	v_mov_b32_e32 v69, v50
	v_pk_mul_f32 v[78:79], v[66:67], v[68:69]
	v_mov_b32_e32 v66, v53
	v_add_f32_e32 v50, v78, v79
	v_mov_b32_e32 v69, v51
	v_mul_f32_e32 v52, v75, v50
	v_pk_mul_f32 v[50:51], v[66:67], v[68:69]
	v_mov_b32_e32 v66, v54
	v_add_f32_e32 v50, v50, v51
	v_mul_f32_e32 v51, v75, v50
	v_cvt_pk_bf16_f32 v232, v77, v80
	v_cvt_pk_bf16_f32 v233, v52, v51
	v_bfe_u32 v236, v224, 5, 1
	v_lshlrev_b32_e32 v236, 3, v236
	v_mov_b32_e32 v237, 0
	v_lshl_add_u64 v[72:73], v[72:73], 0, v[236:237]
	s_waitcnt lgkmcnt(0)
	ds_read2st64_b32 v[50:51], v76 offset0:6 offset1:7
	v_mov_b32_e32 v69, v246
	v_pk_mul_f32 v[52:53], v[66:67], v[68:69]
	v_mov_b32_e32 v66, v55
	v_add_f32_e32 v246, v52, v53
	v_mov_b32_e32 v69, v247
	v_mul_f32_e32 v54, v75, v246
	v_pk_mul_f32 v[246:247], v[66:67], v[68:69]
	v_mov_b32_e32 v66, v56
	v_add_f32_e32 v246, v246, v247
	v_mul_f32_e32 v55, v75, v246
	s_waitcnt lgkmcnt(0)
; template <int DQ, int TYPE>
; __device__ __forceinline__ void attn_item(PP p, int layer, int b, int h, int qt, char* lds, const int tid_, unsigned* next_ctr, volatile XLAS unsigned* slot) {
;     ...
;         if (kh == 0) A_MERGE(0); else A_MERGE(2);
	ds_read2st64_b32 v[246:247], v76 offset0:8 offset1:9
	v_mov_b32_e32 v69, v50
	v_pk_mul_f32 v[52:53], v[66:67], v[68:69]
	v_mov_b32_e32 v66, v57
	v_add_f32_e32 v50, v52, v53
	v_mov_b32_e32 v69, v51
	v_mul_f32_e32 v52, v75, v50
	v_pk_mul_f32 v[50:51], v[66:67], v[68:69]
	v_mov_b32_e32 v66, v58
	v_add_f32_e32 v50, v50, v51
	v_mul_f32_e32 v51, v75, v50
	v_cvt_pk_bf16_f32 v234, v54, v55
	v_cvt_pk_bf16_f32 v235, v52, v51
	s_nop 1
	v_permlane32_swap_b32_e32 v232, v234
	v_permlane32_swap_b32_e32 v233, v235
	global_store_dwordx4 v[72:73], v[232:235], off offset:128
	s_waitcnt lgkmcnt(0)
	ds_read2st64_b32 v[50:51], v76 offset0:10 offset1:11
	v_mov_b32_e32 v69, v246
	v_pk_mul_f32 v[52:53], v[66:67], v[68:69]
	v_mov_b32_e32 v66, v59
	v_add_f32_e32 v246, v52, v53
	v_mov_b32_e32 v69, v247
	v_mul_f32_e32 v54, v75, v246
	v_pk_mul_f32 v[246:247], v[66:67], v[68:69]
	v_mov_b32_e32 v66, v60
	v_add_f32_e32 v246, v246, v247
	v_mul_f32_e32 v55, v75, v246
	s_waitcnt lgkmcnt(0)
	ds_read2st64_b32 v[246:247], v76 offset0:12 offset1:13
	v_mov_b32_e32 v69, v50
	v_pk_mul_f32 v[52:53], v[66:67], v[68:69]
	v_mov_b32_e32 v66, v61
	v_add_f32_e32 v50, v52, v53
	v_mov_b32_e32 v69, v51
	v_mul_f32_e32 v52, v75, v50
	v_pk_mul_f32 v[50:51], v[66:67], v[68:69]
	v_mov_b32_e32 v66, v62
	v_add_f32_e32 v50, v50, v51
	v_mul_f32_e32 v51, v75, v50
	v_cvt_pk_bf16_f32 v232, v54, v55
	v_cvt_pk_bf16_f32 v233, v52, v51
	s_waitcnt lgkmcnt(0)
	ds_read2st64_b32 v[50:51], v76 offset0:14 offset1:15
	v_mov_b32_e32 v69, v246
	v_pk_mul_f32 v[52:53], v[66:67], v[68:69]
	v_mov_b32_e32 v66, v63
	v_add_f32_e32 v246, v52, v53
	v_mov_b32_e32 v69, v247
	v_mul_f32_e32 v54, v75, v246
	v_pk_mul_f32 v[246:247], v[66:67], v[68:69]
	v_mov_b32_e32 v66, v64
	v_add_f32_e32 v246, v246, v247
	v_mul_f32_e32 v55, v75, v246
	s_waitcnt lgkmcnt(0)
	ds_read2st64_b32 v[246:247], v76 offset0:16 offset1:17
	v_mov_b32_e32 v69, v50
	v_pk_mul_f32 v[52:53], v[66:67], v[68:69]
	v_mov_b32_e32 v66, v65
	v_add_f32_e32 v50, v52, v53
	v_mov_b32_e32 v69, v51
	v_mul_f32_e32 v52, v75, v50
	v_pk_mul_f32 v[50:51], v[66:67], v[68:69]
	v_mov_b32_e32 v66, v34
	v_add_f32_e32 v50, v50, v51
	v_mul_f32_e32 v51, v75, v50
	v_cvt_pk_bf16_f32 v234, v54, v55
	v_cvt_pk_bf16_f32 v235, v52, v51
	s_nop 1
	v_permlane32_swap_b32_e32 v232, v234
	v_permlane32_swap_b32_e32 v233, v235
	global_store_dwordx4 v[72:73], v[232:235], off offset:160
	s_waitcnt lgkmcnt(0)
	v_mov_b32_e32 v69, v246
	v_pk_mul_f32 v[52:53], v[66:67], v[68:69]
	v_mov_b32_e32 v66, v35
	v_add_f32_e32 v34, v52, v53
	v_mov_b32_e32 v69, v247
	v_mul_f32_e32 v52, v75, v34
	v_pk_mul_f32 v[34:35], v[66:67], v[68:69]
	v_mov_b32_e32 v66, v36
	v_add_f32_e32 v34, v34, v35
	v_mul_f32_e32 v53, v75, v34
	ds_read2st64_b32 v[34:35], v76 offset0:18 offset1:19
	s_waitcnt lgkmcnt(0)
	ds_read2st64_b32 v[246:247], v76 offset0:20 offset1:21
	v_mov_b32_e32 v69, v34
	v_pk_mul_f32 v[50:51], v[66:67], v[68:69]
	v_mov_b32_e32 v66, v37
	v_add_f32_e32 v34, v50, v51
	v_mov_b32_e32 v69, v35
	v_mul_f32_e32 v36, v75, v34
	v_pk_mul_f32 v[34:35], v[66:67], v[68:69]
	v_mov_b32_e32 v66, v38
	v_add_f32_e32 v34, v34, v35
	v_mul_f32_e32 v35, v75, v34
	v_cvt_pk_bf16_f32 v232, v52, v53
	v_cvt_pk_bf16_f32 v233, v36, v35
	s_waitcnt lgkmcnt(0)
	ds_read2st64_b32 v[34:35], v76 offset0:22 offset1:23
	v_mov_b32_e32 v69, v246
	v_pk_mul_f32 v[36:37], v[66:67], v[68:69]
	v_mov_b32_e32 v66, v39
	v_add_f32_e32 v246, v36, v37
	v_mov_b32_e32 v69, v247
	v_mul_f32_e32 v38, v75, v246
	v_pk_mul_f32 v[246:247], v[66:67], v[68:69]
	v_mov_b32_e32 v66, v40
	v_add_f32_e32 v246, v246, v247
	v_mul_f32_e32 v39, v75, v246
	s_waitcnt lgkmcnt(0)
	ds_read2st64_b32 v[246:247], v76 offset0:24 offset1:25
	v_mov_b32_e32 v69, v34
	v_pk_mul_f32 v[36:37], v[66:67], v[68:69]
	v_mov_b32_e32 v66, v41
	v_add_f32_e32 v34, v36, v37
	v_mov_b32_e32 v69, v35
	v_mul_f32_e32 v36, v75, v34
	v_pk_mul_f32 v[34:35], v[66:67], v[68:69]
	v_mov_b32_e32 v66, v42
	v_add_f32_e32 v34, v34, v35
	v_mul_f32_e32 v35, v75, v34
	v_cvt_pk_bf16_f32 v234, v38, v39
	v_cvt_pk_bf16_f32 v235, v36, v35
	s_nop 1
	v_permlane32_swap_b32_e32 v232, v234
	v_permlane32_swap_b32_e32 v233, v235
	global_store_dwordx4 v[72:73], v[232:235], off offset:192
	s_waitcnt lgkmcnt(0)
	ds_read2st64_b32 v[34:35], v76 offset0:26 offset1:27
	v_mov_b32_e32 v69, v246
	v_pk_mul_f32 v[36:37], v[66:67], v[68:69]
	v_mov_b32_e32 v66, v43
	v_add_f32_e32 v246, v36, v37
	v_mov_b32_e32 v69, v247
	v_mul_f32_e32 v38, v75, v246
	v_pk_mul_f32 v[246:247], v[66:67], v[68:69]
	v_mov_b32_e32 v66, v44
	v_add_f32_e32 v246, v246, v247
	v_mul_f32_e32 v39, v75, v246
	s_waitcnt lgkmcnt(0)
	ds_read2st64_b32 v[246:247], v76 offset0:28 offset1:29
	v_mov_b32_e32 v69, v34
	v_pk_mul_f32 v[36:37], v[66:67], v[68:69]
	v_mov_b32_e32 v66, v45
	v_add_f32_e32 v34, v36, v37
	v_mov_b32_e32 v69, v35
	v_mul_f32_e32 v36, v75, v34
	v_pk_mul_f32 v[34:35], v[66:67], v[68:69]
	v_mov_b32_e32 v66, v46
	v_add_f32_e32 v34, v34, v35
	v_mul_f32_e32 v35, v75, v34
	v_cvt_pk_bf16_f32 v232, v38, v39
	v_cvt_pk_bf16_f32 v233, v36, v35
	s_waitcnt lgkmcnt(0)
	ds_read2st64_b32 v[34:35], v76 offset0:30 offset1:31
	v_mov_b32_e32 v69, v246
	v_pk_mul_f32 v[36:37], v[66:67], v[68:69]
	v_mov_b32_e32 v66, v47
	v_add_f32_e32 v246, v36, v37
	v_mov_b32_e32 v69, v247
	v_mul_f32_e32 v38, v75, v246
	v_pk_mul_f32 v[246:247], v[66:67], v[68:69]
	v_mov_b32_e32 v66, v48
	v_add_f32_e32 v246, v246, v247
	v_mul_f32_e32 v39, v75, v246
	s_waitcnt lgkmcnt(0)
	v_mov_b32_e32 v69, v34
	v_pk_mul_f32 v[36:37], v[66:67], v[68:69]
	v_mov_b32_e32 v66, v49
	v_add_f32_e32 v34, v36, v37
	v_mov_b32_e32 v69, v35
	v_mul_f32_e32 v36, v75, v34
	v_pk_mul_f32 v[34:35], v[66:67], v[68:69]
	s_nop 0
	v_add_f32_e32 v34, v34, v35
	v_mul_f32_e32 v35, v75, v34
	v_cvt_pk_bf16_f32 v234, v38, v39
	v_cvt_pk_bf16_f32 v235, v36, v35
	s_nop 1
	v_permlane32_swap_b32_e32 v232, v234
	v_permlane32_swap_b32_e32 v233, v235
	global_store_dwordx4 v[72:73], v[232:235], off offset:224
	s_cbranch_execz .LBB0_685

; template <int DQ, int TYPE>
; __device__ __forceinline__ void attn_item(PP p, int layer, int b, int h, int qt, char* lds, const int tid_, unsigned* next_ctr, volatile XLAS unsigned* slot) {
;     ...
;         bf16_t* orow = Op + (size_t)qpos * D;
;     ...
;         if (kh == 0) A_MERGE(0); else A_MERGE(2);
.LBB0_681:
	ds_read2st64_b32 v[8:9], v12 offset1:1
	v_mov_b32_e32 v2, v32
	v_lshl_add_u64 v[6:7], v[6:7], 0, v[0:1]
	s_waitcnt lgkmcnt(0)
	ds_read2st64_b32 v[246:247], v12 offset0:2 offset1:3
	v_mov_b32_e32 v5, v8
	v_pk_mul_f32 v[14:15], v[2:3], v[4:5]
	v_mov_b32_e32 v2, v33
	v_mov_b32_e32 v5, v9
	v_pk_mul_f32 v[8:9], v[2:3], v[4:5]
	v_add_f32_e32 v0, v14, v15
	v_add_f32_e32 v2, v8, v9
	v_mul_f32_e32 v13, v11, v2
	v_mov_b32_e32 v2, v34
	v_mul_f32_e32 v0, v11, v0
	s_waitcnt lgkmcnt(0)
	ds_read2st64_b32 v[8:9], v12 offset0:4 offset1:5
	v_mov_b32_e32 v5, v246
	v_pk_mul_f32 v[14:15], v[2:3], v[4:5]
	v_mov_b32_e32 v5, v247
	v_add_f32_e32 v2, v14, v15
	v_mul_f32_e32 v14, v11, v2
	v_mov_b32_e32 v2, v35
	v_pk_mul_f32 v[246:247], v[2:3], v[4:5]
	s_nop 0
	v_add_f32_e32 v2, v246, v247
	v_mul_f32_e32 v2, v11, v2
	v_cvt_pk_bf16_f32 v232, v0, v13
	v_cvt_pk_bf16_f32 v233, v14, v2
	v_bfe_u32 v236, v224, 5, 1
	v_lshlrev_b32_e32 v236, 3, v236
	v_mov_b32_e32 v237, 0
	v_lshl_add_u64 v[6:7], v[6:7], 0, v[236:237]
	v_mov_b32_e32 v2, v36
	s_waitcnt lgkmcnt(0)
	ds_read2st64_b32 v[246:247], v12 offset0:6 offset1:7
	v_mov_b32_e32 v5, v8
	v_pk_mul_f32 v[14:15], v[2:3], v[4:5]
	v_mov_b32_e32 v2, v37
	v_mov_b32_e32 v5, v9
	v_pk_mul_f32 v[8:9], v[2:3], v[4:5]
	v_add_f32_e32 v0, v14, v15
	v_add_f32_e32 v2, v8, v9
	v_mul_f32_e32 v13, v11, v2
	v_mov_b32_e32 v2, v38
	v_mul_f32_e32 v0, v11, v0
	s_waitcnt lgkmcnt(0)
	ds_read2st64_b32 v[8:9], v12 offset0:8 offset1:9
	v_mov_b32_e32 v5, v246
	v_pk_mul_f32 v[14:15], v[2:3], v[4:5]
	v_mov_b32_e32 v5, v247
	v_add_f32_e32 v2, v14, v15
	v_mul_f32_e32 v14, v11, v2
	v_mov_b32_e32 v2, v39
	v_pk_mul_f32 v[246:247], v[2:3], v[4:5]
	s_nop 0
	v_add_f32_e32 v2, v246, v247
	v_mul_f32_e32 v2, v11, v2
	v_cvt_pk_bf16_f32 v234, v0, v13
	v_cvt_pk_bf16_f32 v235, v14, v2
	s_nop 1
	v_permlane32_swap_b32_e32 v232, v234
	v_permlane32_swap_b32_e32 v233, v235
	global_store_dwordx4 v[6:7], v[232:235], off
	v_mov_b32_e32 v2, v40
	s_waitcnt lgkmcnt(0)
	ds_read2st64_b32 v[246:247], v12 offset0:10 offset1:11
	v_mov_b32_e32 v5, v8
	v_pk_mul_f32 v[14:15], v[2:3], v[4:5]
	v_mov_b32_e32 v2, v41
	v_mov_b32_e32 v5, v9
	v_pk_mul_f32 v[8:9], v[2:3], v[4:5]
	v_add_f32_e32 v0, v14, v15
	v_add_f32_e32 v2, v8, v9
	v_mul_f32_e32 v13, v11, v2
	v_mov_b32_e32 v2, v42
	v_mul_f32_e32 v0, v11, v0
	s_waitcnt lgkmcnt(0)
	ds_read2st64_b32 v[8:9], v12 offset0:12 offset1:13
	v_mov_b32_e32 v5, v246
	v_pk_mul_f32 v[14:15], v[2:3], v[4:5]
	v_mov_b32_e32 v5, v247
	v_add_f32_e32 v2, v14, v15
	v_mul_f32_e32 v14, v11, v2
	v_mov_b32_e32 v2, v43
	v_pk_mul_f32 v[246:247], v[2:3], v[4:5]
	s_nop 0
	v_add_f32_e32 v2, v246, v247
	v_mul_f32_e32 v2, v11, v2
	v_cvt_pk_bf16_f32 v232, v0, v13
	v_cvt_pk_bf16_f32 v233, v14, v2
	v_mov_b32_e32 v2, v44
	s_waitcnt lgkmcnt(0)
	ds_read2st64_b32 v[246:247], v12 offset0:14 offset1:15
	v_mov_b32_e32 v5, v8
	v_pk_mul_f32 v[14:15], v[2:3], v[4:5]
	v_mov_b32_e32 v2, v45
	v_mov_b32_e32 v5, v9
	v_pk_mul_f32 v[8:9], v[2:3], v[4:5]
	v_add_f32_e32 v0, v14, v15
	v_add_f32_e32 v2, v8, v9
	v_mul_f32_e32 v13, v11, v2
	v_mov_b32_e32 v2, v46
	v_mul_f32_e32 v0, v11, v0
	s_waitcnt lgkmcnt(0)
	ds_read2st64_b32 v[8:9], v12 offset0:16 offset1:17
	v_mov_b32_e32 v5, v246
	v_pk_mul_f32 v[14:15], v[2:3], v[4:5]
	v_mov_b32_e32 v5, v247
	v_add_f32_e32 v2, v14, v15
	v_mul_f32_e32 v14, v11, v2
	v_mov_b32_e32 v2, v47
	v_pk_mul_f32 v[246:247], v[2:3], v[4:5]
	s_nop 0
	v_add_f32_e32 v2, v246, v247
	v_mul_f32_e32 v2, v11, v2
	v_cvt_pk_bf16_f32 v234, v0, v13
	v_cvt_pk_bf16_f32 v235, v14, v2
	s_nop 1
	v_permlane32_swap_b32_e32 v232, v234
	v_permlane32_swap_b32_e32 v233, v235
	global_store_dwordx4 v[6:7], v[232:235], off offset:32
	v_mov_b32_e32 v2, v16
	s_waitcnt lgkmcnt(0)
; template <int DQ, int TYPE>
; __device__ __forceinline__ void attn_item(PP p, int layer, int b, int h, int qt, char* lds, const int tid_, unsigned* next_ctr, volatile XLAS unsigned* slot) {
;     ...
;         if (kh == 0) A_MERGE(0); else A_MERGE(2);
	ds_read2st64_b32 v[246:247], v12 offset0:18 offset1:19
	v_mov_b32_e32 v5, v8
	v_pk_mul_f32 v[14:15], v[2:3], v[4:5]
	v_mov_b32_e32 v2, v17
	v_mov_b32_e32 v5, v9
	v_pk_mul_f32 v[8:9], v[2:3], v[4:5]
	v_add_f32_e32 v0, v14, v15
	v_add_f32_e32 v2, v8, v9
	v_mul_f32_e32 v13, v11, v2
	v_mov_b32_e32 v2, v18
	v_mul_f32_e32 v0, v11, v0
	s_waitcnt lgkmcnt(0)
	ds_read2st64_b32 v[8:9], v12 offset0:20 offset1:21
	v_mov_b32_e32 v5, v246
	v_pk_mul_f32 v[14:15], v[2:3], v[4:5]
	v_mov_b32_e32 v5, v247
	v_add_f32_e32 v2, v14, v15
	v_mul_f32_e32 v14, v11, v2
	v_mov_b32_e32 v2, v19
	v_pk_mul_f32 v[246:247], v[2:3], v[4:5]
	s_nop 0
	v_add_f32_e32 v2, v246, v247
	v_mul_f32_e32 v2, v11, v2
	v_cvt_pk_bf16_f32 v232, v0, v13
	v_cvt_pk_bf16_f32 v233, v14, v2
	v_mov_b32_e32 v2, v20
	s_waitcnt lgkmcnt(0)
	ds_read2st64_b32 v[246:247], v12 offset0:22 offset1:23
	v_mov_b32_e32 v5, v8
	v_pk_mul_f32 v[14:15], v[2:3], v[4:5]
	v_mov_b32_e32 v2, v21
	v_mov_b32_e32 v5, v9
	v_pk_mul_f32 v[8:9], v[2:3], v[4:5]
	v_add_f32_e32 v0, v14, v15
	v_add_f32_e32 v2, v8, v9
	v_mul_f32_e32 v13, v11, v2
	v_mov_b32_e32 v2, v22
	v_mul_f32_e32 v0, v11, v0
	s_waitcnt lgkmcnt(0)
	ds_read2st64_b32 v[8:9], v12 offset0:24 offset1:25
	v_mov_b32_e32 v5, v246
	v_pk_mul_f32 v[14:15], v[2:3], v[4:5]
	v_mov_b32_e32 v5, v247
	v_add_f32_e32 v2, v14, v15
	v_mul_f32_e32 v14, v11, v2
	v_mov_b32_e32 v2, v23
	v_pk_mul_f32 v[246:247], v[2:3], v[4:5]
	s_nop 0
	v_add_f32_e32 v2, v246, v247
	v_mul_f32_e32 v2, v11, v2
	v_cvt_pk_bf16_f32 v234, v0, v13
	v_cvt_pk_bf16_f32 v235, v14, v2
	s_nop 1
	v_permlane32_swap_b32_e32 v232, v234
	v_permlane32_swap_b32_e32 v233, v235
	global_store_dwordx4 v[6:7], v[232:235], off offset:64
	v_mov_b32_e32 v2, v24
	s_waitcnt lgkmcnt(0)
	ds_read2st64_b32 v[246:247], v12 offset0:26 offset1:27
	v_mov_b32_e32 v5, v8
	v_pk_mul_f32 v[14:15], v[2:3], v[4:5]
	v_mov_b32_e32 v2, v25
	v_mov_b32_e32 v5, v9
	v_pk_mul_f32 v[8:9], v[2:3], v[4:5]
	v_add_f32_e32 v0, v14, v15
	v_add_f32_e32 v2, v8, v9
	v_mul_f32_e32 v13, v11, v2
	v_mov_b32_e32 v2, v26
	v_mul_f32_e32 v0, v11, v0
	s_waitcnt lgkmcnt(0)
	ds_read2st64_b32 v[8:9], v12 offset0:28 offset1:29
	v_mov_b32_e32 v5, v246
	v_pk_mul_f32 v[14:15], v[2:3], v[4:5]
	v_mov_b32_e32 v5, v247
	v_add_f32_e32 v2, v14, v15
	v_mul_f32_e32 v14, v11, v2
	v_mov_b32_e32 v2, v27
	v_pk_mul_f32 v[246:247], v[2:3], v[4:5]
	s_nop 0
	v_add_f32_e32 v2, v246, v247
	v_mul_f32_e32 v2, v11, v2
	v_cvt_pk_bf16_f32 v232, v0, v13
	v_cvt_pk_bf16_f32 v233, v14, v2
	v_mov_b32_e32 v2, v28
	s_waitcnt lgkmcnt(0)
	ds_read2st64_b32 v[246:247], v12 offset0:30 offset1:31
	v_mov_b32_e32 v5, v8
	v_pk_mul_f32 v[14:15], v[2:3], v[4:5]
	v_mov_b32_e32 v2, v29
	v_mov_b32_e32 v5, v9
	v_pk_mul_f32 v[8:9], v[2:3], v[4:5]
	v_add_f32_e32 v0, v14, v15
	v_add_f32_e32 v2, v8, v9
	v_mul_f32_e32 v14, v11, v2
	v_mov_b32_e32 v2, v30
	v_mul_f32_e32 v0, v11, v0
	s_waitcnt lgkmcnt(0)
	v_mov_b32_e32 v5, v246
	v_pk_mul_f32 v[12:13], v[2:3], v[4:5]
	v_mov_b32_e32 v5, v247
	v_add_f32_e32 v2, v12, v13
	v_mul_f32_e32 v246, v11, v2
	v_mov_b32_e32 v2, v31
	v_pk_mul_f32 v[2:3], v[2:3], v[4:5]
	s_nop 0
	v_add_f32_e32 v2, v2, v3
	v_mul_f32_e32 v3, v11, v2
	v_cvt_pk_bf16_f32 v234, v0, v14
	v_cvt_pk_bf16_f32 v235, v246, v3
	s_nop 1
	v_permlane32_swap_b32_e32 v232, v234
	v_permlane32_swap_b32_e32 v233, v235
	global_store_dwordx4 v[6:7], v[232:235], off offset:96
	s_and_saveexec_b64 s[8:9], s[50:51]
	s_cbranch_execnz .LBB0_421
	s_branch .LBB0_422

; template <int DQ, int TYPE>
; __device__ __forceinline__ void attn_item(PP p, int layer, int b, int h, int qt, char* lds, const int tid_, unsigned* next_ctr, volatile XLAS unsigned* slot) {
;     ...
;         bf16_t* orow = Op + (size_t)qpos * D;
;     ...
;         if (kh == 0) A_MERGE(0); else A_MERGE(2);
.LBB0_683:
	ds_read2st64_b32 v[36:37], v76 offset1:1
	v_mov_b32_e32 v66, v18
	v_lshl_add_u64 v[34:35], v[70:71], 0, v[0:1]
	s_waitcnt lgkmcnt(0)
	v_mov_b32_e32 v69, v36
	v_pk_mul_f32 v[38:39], v[66:67], v[68:69]
	v_mov_b32_e32 v66, v19
	v_mov_b32_e32 v69, v37
	v_pk_mul_f32 v[18:19], v[66:67], v[68:69]
	v_add_f32_e32 v0, v38, v39
	v_add_f32_e32 v18, v18, v19
	v_mul_f32_e32 v38, v75, v18
	ds_read2st64_b32 v[18:19], v76 offset0:2 offset1:3
	v_mov_b32_e32 v66, v20
	v_mul_f32_e32 v0, v75, v0
	s_waitcnt lgkmcnt(0)
	ds_read2st64_b32 v[246:247], v76 offset0:4 offset1:5
	v_mov_b32_e32 v69, v18
	v_pk_mul_f32 v[36:37], v[66:67], v[68:69]
	v_mov_b32_e32 v66, v21
	v_add_f32_e32 v18, v36, v37
	v_mov_b32_e32 v69, v19
	v_mul_f32_e32 v20, v75, v18
	v_pk_mul_f32 v[18:19], v[66:67], v[68:69]
	v_mov_b32_e32 v66, v22
	v_add_f32_e32 v18, v18, v19
	v_mul_f32_e32 v19, v75, v18
	v_cvt_pk_bf16_f32 v232, v0, v38
	v_cvt_pk_bf16_f32 v233, v20, v19
	v_bfe_u32 v236, v224, 5, 1
	v_lshlrev_b32_e32 v236, 3, v236
	v_mov_b32_e32 v237, 0
	v_lshl_add_u64 v[34:35], v[34:35], 0, v[236:237]
	s_waitcnt lgkmcnt(0)
	ds_read2st64_b32 v[18:19], v76 offset0:6 offset1:7
	v_mov_b32_e32 v69, v246
	v_pk_mul_f32 v[20:21], v[66:67], v[68:69]
	v_mov_b32_e32 v66, v23
	v_mov_b32_e32 v69, v247
	v_pk_mul_f32 v[246:247], v[66:67], v[68:69]
	v_mov_b32_e32 v66, v24
	v_add_f32_e32 v246, v246, v247
	v_mul_f32_e32 v22, v75, v246
	v_add_f32_e32 v0, v20, v21
	v_mul_f32_e32 v0, v75, v0
	s_waitcnt lgkmcnt(0)
	ds_read2st64_b32 v[246:247], v76 offset0:8 offset1:9
	v_mov_b32_e32 v69, v18
	v_pk_mul_f32 v[20:21], v[66:67], v[68:69]
	v_mov_b32_e32 v66, v25
	v_add_f32_e32 v18, v20, v21
	v_mov_b32_e32 v69, v19
	v_mul_f32_e32 v20, v75, v18
	v_pk_mul_f32 v[18:19], v[66:67], v[68:69]
	v_mov_b32_e32 v66, v26
	v_add_f32_e32 v18, v18, v19
	v_mul_f32_e32 v19, v75, v18
	v_cvt_pk_bf16_f32 v234, v0, v22
	v_cvt_pk_bf16_f32 v235, v20, v19
	s_nop 1
	v_permlane32_swap_b32_e32 v232, v234
	v_permlane32_swap_b32_e32 v233, v235
	global_store_dwordx4 v[34:35], v[232:235], off
	s_waitcnt lgkmcnt(0)
	ds_read2st64_b32 v[18:19], v76 offset0:10 offset1:11
	v_mov_b32_e32 v69, v246
	v_pk_mul_f32 v[20:21], v[66:67], v[68:69]
	v_mov_b32_e32 v66, v27
	v_mov_b32_e32 v69, v247
	v_pk_mul_f32 v[246:247], v[66:67], v[68:69]
	v_mov_b32_e32 v66, v28
	v_add_f32_e32 v246, v246, v247
	v_mul_f32_e32 v22, v75, v246
	v_add_f32_e32 v0, v20, v21
	v_mul_f32_e32 v0, v75, v0
	s_waitcnt lgkmcnt(0)
	ds_read2st64_b32 v[246:247], v76 offset0:12 offset1:13
	v_mov_b32_e32 v69, v18
	v_pk_mul_f32 v[20:21], v[66:67], v[68:69]
	v_mov_b32_e32 v66, v29
	v_add_f32_e32 v18, v20, v21
	v_mov_b32_e32 v69, v19
	v_mul_f32_e32 v20, v75, v18
	v_pk_mul_f32 v[18:19], v[66:67], v[68:69]
	v_mov_b32_e32 v66, v30
	v_add_f32_e32 v18, v18, v19
	v_mul_f32_e32 v19, v75, v18
	v_cvt_pk_bf16_f32 v232, v0, v22
	v_cvt_pk_bf16_f32 v233, v20, v19
	s_waitcnt lgkmcnt(0)
	ds_read2st64_b32 v[18:19], v76 offset0:14 offset1:15
	v_mov_b32_e32 v69, v246
	v_pk_mul_f32 v[20:21], v[66:67], v[68:69]
	v_mov_b32_e32 v66, v31
	v_mov_b32_e32 v69, v247
	v_pk_mul_f32 v[246:247], v[66:67], v[68:69]
	v_mov_b32_e32 v66, v32
	v_add_f32_e32 v246, v246, v247
	v_mul_f32_e32 v22, v75, v246
	v_add_f32_e32 v0, v20, v21
	v_mul_f32_e32 v0, v75, v0
	s_waitcnt lgkmcnt(0)
	ds_read2st64_b32 v[246:247], v76 offset0:16 offset1:17
	v_mov_b32_e32 v69, v18
	v_pk_mul_f32 v[20:21], v[66:67], v[68:69]
	v_mov_b32_e32 v66, v33
	v_add_f32_e32 v18, v20, v21
	v_mov_b32_e32 v69, v19
	v_mul_f32_e32 v20, v75, v18
	v_pk_mul_f32 v[18:19], v[66:67], v[68:69]
	v_mov_b32_e32 v66, v2
	v_add_f32_e32 v18, v18, v19
	v_mul_f32_e32 v19, v75, v18
	v_cvt_pk_bf16_f32 v234, v0, v22
	v_cvt_pk_bf16_f32 v235, v20, v19
	s_nop 1
	v_permlane32_swap_b32_e32 v232, v234
	v_permlane32_swap_b32_e32 v233, v235
	global_store_dwordx4 v[34:35], v[232:235], off offset:32
	s_waitcnt lgkmcnt(0)
; template <int DQ, int TYPE>
; __device__ __forceinline__ void attn_item(PP p, int layer, int b, int h, int qt, char* lds, const int tid_, unsigned* next_ctr, volatile XLAS unsigned* slot) {
;     ...
;         if (kh == 0) A_MERGE(0); else A_MERGE(2);
	v_mov_b32_e32 v69, v246
	v_pk_mul_f32 v[20:21], v[66:67], v[68:69]
	v_mov_b32_e32 v66, v3
	v_mov_b32_e32 v69, v247
	v_pk_mul_f32 v[2:3], v[66:67], v[68:69]
	v_add_f32_e32 v0, v20, v21
	v_add_f32_e32 v2, v2, v3
	v_mul_f32_e32 v20, v75, v2
	ds_read2st64_b32 v[2:3], v76 offset0:18 offset1:19
	v_mov_b32_e32 v66, v4
	v_mul_f32_e32 v0, v75, v0
	s_waitcnt lgkmcnt(0)
	ds_read2st64_b32 v[246:247], v76 offset0:20 offset1:21
	v_mov_b32_e32 v69, v2
	v_pk_mul_f32 v[18:19], v[66:67], v[68:69]
	v_mov_b32_e32 v66, v5
	v_add_f32_e32 v2, v18, v19
	v_mov_b32_e32 v69, v3
	v_mul_f32_e32 v4, v75, v2
	v_pk_mul_f32 v[2:3], v[66:67], v[68:69]
	v_mov_b32_e32 v66, v6
	v_add_f32_e32 v2, v2, v3
	v_mul_f32_e32 v3, v75, v2
	v_cvt_pk_bf16_f32 v232, v0, v20
	v_cvt_pk_bf16_f32 v233, v4, v3
	s_waitcnt lgkmcnt(0)
	ds_read2st64_b32 v[2:3], v76 offset0:22 offset1:23
	v_mov_b32_e32 v69, v246
	v_pk_mul_f32 v[4:5], v[66:67], v[68:69]
	v_mov_b32_e32 v66, v7
	v_mov_b32_e32 v69, v247
	v_pk_mul_f32 v[246:247], v[66:67], v[68:69]
	v_mov_b32_e32 v66, v8
	v_add_f32_e32 v246, v246, v247
	v_mul_f32_e32 v6, v75, v246
	v_add_f32_e32 v0, v4, v5
	v_mul_f32_e32 v0, v75, v0
	s_waitcnt lgkmcnt(0)
	ds_read2st64_b32 v[246:247], v76 offset0:24 offset1:25
	v_mov_b32_e32 v69, v2
	v_pk_mul_f32 v[4:5], v[66:67], v[68:69]
	v_mov_b32_e32 v66, v9
	v_add_f32_e32 v2, v4, v5
	v_mov_b32_e32 v69, v3
	v_mul_f32_e32 v4, v75, v2
	v_pk_mul_f32 v[2:3], v[66:67], v[68:69]
	v_mov_b32_e32 v66, v10
	v_add_f32_e32 v2, v2, v3
	v_mul_f32_e32 v3, v75, v2
	v_cvt_pk_bf16_f32 v234, v0, v6
	v_cvt_pk_bf16_f32 v235, v4, v3
	s_nop 1
	v_permlane32_swap_b32_e32 v232, v234
	v_permlane32_swap_b32_e32 v233, v235
	global_store_dwordx4 v[34:35], v[232:235], off offset:64
	s_waitcnt lgkmcnt(0)
	ds_read2st64_b32 v[2:3], v76 offset0:26 offset1:27
	v_mov_b32_e32 v69, v246
	v_pk_mul_f32 v[4:5], v[66:67], v[68:69]
	v_mov_b32_e32 v66, v11
	v_mov_b32_e32 v69, v247
	v_pk_mul_f32 v[246:247], v[66:67], v[68:69]
	v_mov_b32_e32 v66, v12
	v_add_f32_e32 v246, v246, v247
	v_mul_f32_e32 v6, v75, v246
	v_add_f32_e32 v0, v4, v5
	v_mul_f32_e32 v0, v75, v0
	s_waitcnt lgkmcnt(0)
	ds_read2st64_b32 v[246:247], v76 offset0:28 offset1:29
	v_mov_b32_e32 v69, v2
	v_pk_mul_f32 v[4:5], v[66:67], v[68:69]
	v_mov_b32_e32 v66, v13
	v_add_f32_e32 v2, v4, v5
	v_mov_b32_e32 v69, v3
	v_mul_f32_e32 v4, v75, v2
	v_pk_mul_f32 v[2:3], v[66:67], v[68:69]
	v_mov_b32_e32 v66, v14
	v_add_f32_e32 v2, v2, v3
	v_mul_f32_e32 v3, v75, v2
	v_cvt_pk_bf16_f32 v232, v0, v6
	v_cvt_pk_bf16_f32 v233, v4, v3
	s_waitcnt lgkmcnt(0)
	ds_read2st64_b32 v[2:3], v76 offset0:30 offset1:31
	v_mov_b32_e32 v69, v246
	v_pk_mul_f32 v[4:5], v[66:67], v[68:69]
	v_mov_b32_e32 v66, v15
	v_mov_b32_e32 v69, v247
	v_pk_mul_f32 v[246:247], v[66:67], v[68:69]
	v_mov_b32_e32 v66, v16
	v_add_f32_e32 v246, v246, v247
	v_mul_f32_e32 v6, v75, v246
	v_add_f32_e32 v0, v4, v5
	v_mul_f32_e32 v0, v75, v0
	s_waitcnt lgkmcnt(0)
	v_mov_b32_e32 v69, v2
	v_pk_mul_f32 v[4:5], v[66:67], v[68:69]
	v_mov_b32_e32 v66, v17
	v_add_f32_e32 v2, v4, v5
	v_mov_b32_e32 v69, v3
	v_mul_f32_e32 v4, v75, v2
	v_pk_mul_f32 v[2:3], v[66:67], v[68:69]
	s_nop 0
	v_add_f32_e32 v2, v2, v3
	v_mul_f32_e32 v3, v75, v2
	v_cvt_pk_bf16_f32 v234, v0, v6
	v_cvt_pk_bf16_f32 v235, v4, v3
	s_nop 1
	v_permlane32_swap_b32_e32 v232, v234
	v_permlane32_swap_b32_e32 v233, v235
	global_store_dwordx4 v[34:35], v[232:235], off offset:96
	s_and_saveexec_b64 s[8:9], s[50:51]
	s_cbranch_execnz .LBB0_656
	s_branch .LBB0_657

; template <int DQ, int TYPE>
; __device__ __forceinline__ void attn_item(PP p, int layer, int b, int h, int qt, char* lds, const int tid_, unsigned* next_ctr, volatile XLAS unsigned* slot) {
;     ...
;         bf16_t* orow = Op + (size_t)qpos * D;
;     ...
;         if (kh == 0) A_MERGE(0); else A_MERGE(2);
.LBB0_685:
	ds_read2st64_b32 v[36:37], v76 offset1:1
	v_mov_b32_e32 v66, v18
	v_lshl_add_u64 v[34:35], v[70:71], 0, v[0:1]
	s_waitcnt lgkmcnt(0)
	v_mov_b32_e32 v69, v36
	v_pk_mul_f32 v[38:39], v[66:67], v[68:69]
	v_mov_b32_e32 v66, v19
	v_mov_b32_e32 v69, v37
	v_pk_mul_f32 v[18:19], v[66:67], v[68:69]
	v_add_f32_e32 v0, v38, v39
	v_add_f32_e32 v18, v18, v19
	v_mul_f32_e32 v38, v75, v18
	ds_read2st64_b32 v[18:19], v76 offset0:2 offset1:3
	v_mov_b32_e32 v66, v20
	v_mul_f32_e32 v0, v75, v0
	s_waitcnt lgkmcnt(0)
	ds_read2st64_b32 v[246:247], v76 offset0:4 offset1:5
	v_mov_b32_e32 v69, v18
	v_pk_mul_f32 v[36:37], v[66:67], v[68:69]
	v_mov_b32_e32 v66, v21
	v_add_f32_e32 v18, v36, v37
	v_mov_b32_e32 v69, v19
	v_mul_f32_e32 v20, v75, v18
	v_pk_mul_f32 v[18:19], v[66:67], v[68:69]
	v_mov_b32_e32 v66, v22
	v_add_f32_e32 v18, v18, v19
	v_mul_f32_e32 v19, v75, v18
	v_cvt_pk_bf16_f32 v232, v0, v38
	v_cvt_pk_bf16_f32 v233, v20, v19
	v_bfe_u32 v236, v224, 5, 1
	v_lshlrev_b32_e32 v236, 3, v236
	v_mov_b32_e32 v237, 0
	v_lshl_add_u64 v[34:35], v[34:35], 0, v[236:237]
	s_waitcnt lgkmcnt(0)
	ds_read2st64_b32 v[18:19], v76 offset0:6 offset1:7
	v_mov_b32_e32 v69, v246
	v_pk_mul_f32 v[20:21], v[66:67], v[68:69]
	v_mov_b32_e32 v66, v23
	v_mov_b32_e32 v69, v247
	v_pk_mul_f32 v[246:247], v[66:67], v[68:69]
	v_mov_b32_e32 v66, v24
	v_add_f32_e32 v246, v246, v247
	v_mul_f32_e32 v22, v75, v246
	v_add_f32_e32 v0, v20, v21
	v_mul_f32_e32 v0, v75, v0
	s_waitcnt lgkmcnt(0)
	ds_read2st64_b32 v[246:247], v76 offset0:8 offset1:9
	v_mov_b32_e32 v69, v18
	v_pk_mul_f32 v[20:21], v[66:67], v[68:69]
	v_mov_b32_e32 v66, v25
	v_add_f32_e32 v18, v20, v21
	v_mov_b32_e32 v69, v19
	v_mul_f32_e32 v20, v75, v18
	v_pk_mul_f32 v[18:19], v[66:67], v[68:69]
	v_mov_b32_e32 v66, v26
	v_add_f32_e32 v18, v18, v19
	v_mul_f32_e32 v19, v75, v18
	v_cvt_pk_bf16_f32 v234, v0, v22
	v_cvt_pk_bf16_f32 v235, v20, v19
	s_nop 1
	v_permlane32_swap_b32_e32 v232, v234
	v_permlane32_swap_b32_e32 v233, v235
	global_store_dwordx4 v[34:35], v[232:235], off
	s_waitcnt lgkmcnt(0)
	ds_read2st64_b32 v[18:19], v76 offset0:10 offset1:11
	v_mov_b32_e32 v69, v246
	v_pk_mul_f32 v[20:21], v[66:67], v[68:69]
	v_mov_b32_e32 v66, v27
	v_mov_b32_e32 v69, v247
	v_pk_mul_f32 v[246:247], v[66:67], v[68:69]
	v_mov_b32_e32 v66, v28
	v_add_f32_e32 v246, v246, v247
	v_mul_f32_e32 v22, v75, v246
	v_add_f32_e32 v0, v20, v21
	v_mul_f32_e32 v0, v75, v0
	s_waitcnt lgkmcnt(0)
	ds_read2st64_b32 v[246:247], v76 offset0:12 offset1:13
	v_mov_b32_e32 v69, v18
	v_pk_mul_f32 v[20:21], v[66:67], v[68:69]
	v_mov_b32_e32 v66, v29
	v_add_f32_e32 v18, v20, v21
	v_mov_b32_e32 v69, v19
	v_mul_f32_e32 v20, v75, v18
	v_pk_mul_f32 v[18:19], v[66:67], v[68:69]
	v_mov_b32_e32 v66, v30
	v_add_f32_e32 v18, v18, v19
	v_mul_f32_e32 v19, v75, v18
	v_cvt_pk_bf16_f32 v232, v0, v22
	v_cvt_pk_bf16_f32 v233, v20, v19
	s_waitcnt lgkmcnt(0)
	ds_read2st64_b32 v[18:19], v76 offset0:14 offset1:15
	v_mov_b32_e32 v69, v246
	v_pk_mul_f32 v[20:21], v[66:67], v[68:69]
	v_mov_b32_e32 v66, v31
	v_mov_b32_e32 v69, v247
	v_pk_mul_f32 v[246:247], v[66:67], v[68:69]
	v_mov_b32_e32 v66, v32
	v_add_f32_e32 v246, v246, v247
	v_mul_f32_e32 v22, v75, v246
	v_add_f32_e32 v0, v20, v21
	v_mul_f32_e32 v0, v75, v0
	s_waitcnt lgkmcnt(0)
	ds_read2st64_b32 v[246:247], v76 offset0:16 offset1:17
	v_mov_b32_e32 v69, v18
	v_pk_mul_f32 v[20:21], v[66:67], v[68:69]
	v_mov_b32_e32 v66, v33
	v_add_f32_e32 v18, v20, v21
	v_mov_b32_e32 v69, v19
	v_mul_f32_e32 v20, v75, v18
	v_pk_mul_f32 v[18:19], v[66:67], v[68:69]
	v_mov_b32_e32 v66, v2
	v_add_f32_e32 v18, v18, v19
	v_mul_f32_e32 v19, v75, v18
	v_cvt_pk_bf16_f32 v234, v0, v22
	v_cvt_pk_bf16_f32 v235, v20, v19
	s_nop 1
	v_permlane32_swap_b32_e32 v232, v234
	v_permlane32_swap_b32_e32 v233, v235
	global_store_dwordx4 v[34:35], v[232:235], off offset:32
	s_waitcnt lgkmcnt(0)
; template <int DQ, int TYPE>
; __device__ __forceinline__ void attn_item(PP p, int layer, int b, int h, int qt, char* lds, const int tid_, unsigned* next_ctr, volatile XLAS unsigned* slot) {
;     ...
;         if (kh == 0) A_MERGE(0); else A_MERGE(2);
	v_mov_b32_e32 v69, v246
	v_pk_mul_f32 v[20:21], v[66:67], v[68:69]
	v_mov_b32_e32 v66, v3
	v_mov_b32_e32 v69, v247
	v_pk_mul_f32 v[2:3], v[66:67], v[68:69]
	v_add_f32_e32 v0, v20, v21
	v_add_f32_e32 v2, v2, v3
	v_mul_f32_e32 v20, v75, v2
	ds_read2st64_b32 v[2:3], v76 offset0:18 offset1:19
	v_mov_b32_e32 v66, v4
	v_mul_f32_e32 v0, v75, v0
	s_waitcnt lgkmcnt(0)
	ds_read2st64_b32 v[246:247], v76 offset0:20 offset1:21
	v_mov_b32_e32 v69, v2
	v_pk_mul_f32 v[18:19], v[66:67], v[68:69]
	v_mov_b32_e32 v66, v5
	v_add_f32_e32 v2, v18, v19
	v_mov_b32_e32 v69, v3
	v_mul_f32_e32 v4, v75, v2
	v_pk_mul_f32 v[2:3], v[66:67], v[68:69]
	v_mov_b32_e32 v66, v6
	v_add_f32_e32 v2, v2, v3
	v_mul_f32_e32 v3, v75, v2
	v_cvt_pk_bf16_f32 v232, v0, v20
	v_cvt_pk_bf16_f32 v233, v4, v3
	s_waitcnt lgkmcnt(0)
	ds_read2st64_b32 v[2:3], v76 offset0:22 offset1:23
	v_mov_b32_e32 v69, v246
	v_pk_mul_f32 v[4:5], v[66:67], v[68:69]
	v_mov_b32_e32 v66, v7
	v_mov_b32_e32 v69, v247
	v_pk_mul_f32 v[246:247], v[66:67], v[68:69]
	v_mov_b32_e32 v66, v8
	v_add_f32_e32 v246, v246, v247
	v_mul_f32_e32 v6, v75, v246
	v_add_f32_e32 v0, v4, v5
	v_mul_f32_e32 v0, v75, v0
	s_waitcnt lgkmcnt(0)
	ds_read2st64_b32 v[246:247], v76 offset0:24 offset1:25
	v_mov_b32_e32 v69, v2
	v_pk_mul_f32 v[4:5], v[66:67], v[68:69]
	v_mov_b32_e32 v66, v9
	v_add_f32_e32 v2, v4, v5
	v_mov_b32_e32 v69, v3
	v_mul_f32_e32 v4, v75, v2
	v_pk_mul_f32 v[2:3], v[66:67], v[68:69]
	v_mov_b32_e32 v66, v10
	v_add_f32_e32 v2, v2, v3
	v_mul_f32_e32 v3, v75, v2
	v_cvt_pk_bf16_f32 v234, v0, v6
	v_cvt_pk_bf16_f32 v235, v4, v3
	s_nop 1
	v_permlane32_swap_b32_e32 v232, v234
	v_permlane32_swap_b32_e32 v233, v235
	global_store_dwordx4 v[34:35], v[232:235], off offset:64
	s_waitcnt lgkmcnt(0)
	ds_read2st64_b32 v[2:3], v76 offset0:26 offset1:27
	v_mov_b32_e32 v69, v246
	v_pk_mul_f32 v[4:5], v[66:67], v[68:69]
	v_mov_b32_e32 v66, v11
	v_mov_b32_e32 v69, v247
	v_pk_mul_f32 v[246:247], v[66:67], v[68:69]
	v_mov_b32_e32 v66, v12
	v_add_f32_e32 v246, v246, v247
	v_mul_f32_e32 v6, v75, v246
	v_add_f32_e32 v0, v4, v5
	v_mul_f32_e32 v0, v75, v0
	s_waitcnt lgkmcnt(0)
	ds_read2st64_b32 v[246:247], v76 offset0:28 offset1:29
	v_mov_b32_e32 v69, v2
	v_pk_mul_f32 v[4:5], v[66:67], v[68:69]
	v_mov_b32_e32 v66, v13
	v_add_f32_e32 v2, v4, v5
	v_mov_b32_e32 v69, v3
	v_mul_f32_e32 v4, v75, v2
	v_pk_mul_f32 v[2:3], v[66:67], v[68:69]
	v_mov_b32_e32 v66, v14
	v_add_f32_e32 v2, v2, v3
	v_mul_f32_e32 v3, v75, v2
	v_cvt_pk_bf16_f32 v232, v0, v6
	v_cvt_pk_bf16_f32 v233, v4, v3
	s_waitcnt lgkmcnt(0)
	ds_read2st64_b32 v[2:3], v76 offset0:30 offset1:31
	v_mov_b32_e32 v69, v246
	v_pk_mul_f32 v[4:5], v[66:67], v[68:69]
	v_mov_b32_e32 v66, v15
	v_mov_b32_e32 v69, v247
	v_pk_mul_f32 v[246:247], v[66:67], v[68:69]
	v_mov_b32_e32 v66, v16
	v_add_f32_e32 v246, v246, v247
	v_mul_f32_e32 v6, v75, v246
	v_add_f32_e32 v0, v4, v5
	v_mul_f32_e32 v0, v75, v0
	s_waitcnt lgkmcnt(0)
	v_mov_b32_e32 v69, v2
	v_pk_mul_f32 v[4:5], v[66:67], v[68:69]
	v_mov_b32_e32 v66, v17
	v_add_f32_e32 v2, v4, v5
	v_mov_b32_e32 v69, v3
	v_mul_f32_e32 v4, v75, v2
	v_pk_mul_f32 v[2:3], v[66:67], v[68:69]
	s_nop 0
	v_add_f32_e32 v2, v2, v3
	v_mul_f32_e32 v3, v75, v2
	v_cvt_pk_bf16_f32 v234, v0, v6
	v_cvt_pk_bf16_f32 v235, v4, v3
	s_nop 1
	v_permlane32_swap_b32_e32 v232, v234
	v_permlane32_swap_b32_e32 v233, v235
	global_store_dwordx4 v[34:35], v[232:235], off offset:96
	s_and_saveexec_b64 s[8:9], s[50:51]
	s_cbranch_execz .LBB0_384
